# residual GEMM epilogues (4 sites): 32+32 dwordx2 loads/stores -> 16+16 dwordx4 via v_permlane16_swap row-block pairing
# speedup vs baseline: 1.0159x; 1.0159x over previous
.LBB0_568:
	s_or_b64 exec, exec, s[44:45]
	s_lshl_b32 s98, s40, 1
	s_lshl_b32 s99, s42, 11
	s_add_i32 s98, s98, s99
	v_lshlrev_b32_e32 v132, 6, v146
	v_lshl_add_u32 v132, v147, 3, v132
	v_lshl_add_u32 v132, v148, 11, v132
	v_lshl_add_u32 v132, v145, 17, v132
	v_add_u32_e32 v132, s98, v132
	v_add_u32_e32 v133, 0x8000, v132
	v_add_u32_e32 v134, 0x10000, v132
	v_add_u32_e32 v135, 0x18000, v132
	v_add_u32_e32 v136, 0x40000, v132
	v_add_u32_e32 v137, 0x48000, v132
	v_add_u32_e32 v138, 0x50000, v132
	v_add_u32_e32 v139, 0x58000, v132
	v_bfe_u32 v133, v154, 4, 1
	v_mul_u32_u24_e32 v133, 0x7ff8, v133
	v_add_u32_e32 v132, v132, v133
	v_add_u32_e32 v134, v134, v133
	v_add_u32_e32 v136, v136, v133
	v_add_u32_e32 v138, v138, v133
	global_load_dwordx4 v[176:179], v132, s[6:7]
	global_load_dwordx4 v[180:183], v132, s[6:7] offset:32
	global_load_dwordx4 v[184:187], v132, s[6:7] offset:256
	global_load_dwordx4 v[188:191], v132, s[6:7] offset:288
	global_load_dwordx4 v[192:195], v134, s[6:7]
	global_load_dwordx4 v[196:199], v134, s[6:7] offset:32
	global_load_dwordx4 v[200:203], v134, s[6:7] offset:256
	global_load_dwordx4 v[204:207], v134, s[6:7] offset:288
	global_load_dwordx4 v[208:211], v136, s[6:7]
	global_load_dwordx4 v[212:215], v136, s[6:7] offset:32
	global_load_dwordx4 v[216:219], v136, s[6:7] offset:256
	global_load_dwordx4 v[220:223], v136, s[6:7] offset:288
	global_load_dwordx4 v[224:227], v138, s[6:7]
	global_load_dwordx4 v[228:231], v138, s[6:7] offset:32
	global_load_dwordx4 v[232:235], v138, s[6:7] offset:256
	global_load_dwordx4 v[236:239], v138, s[6:7] offset:288
	s_waitcnt vmcnt(15)
	v_permlane16_swap_b32_e32 v176, v178
	v_permlane16_swap_b32_e32 v177, v179
	s_nop 0
	v_lshlrev_b32_e32 v140, 16, v177
	v_and_b32_e32 v141, 0xffff0000, v177
	v_and_b32_e32 v177, 0xffff0000, v176
	v_lshlrev_b32_e32 v176, 16, v176
	v_lshlrev_b32_e32 v142, 16, v179
	v_and_b32_e32 v143, 0xffff0000, v179
	v_and_b32_e32 v179, 0xffff0000, v178
	v_lshlrev_b32_e32 v178, 16, v178
	v_pk_fma_f32 v[124:125], v[176:177], s[38:39], v[124:125] op_sel_hi:[1,0,1]
	v_pk_fma_f32 v[126:127], v[140:141], s[38:39], v[126:127] op_sel_hi:[1,0,1]
	v_pk_fma_f32 v[112:113], v[178:179], s[38:39], v[112:113] op_sel_hi:[1,0,1]
	v_pk_fma_f32 v[114:115], v[142:143], s[38:39], v[114:115] op_sel_hi:[1,0,1]
	v_cvt_pk_bf16_f32 v176, v124, v125
	v_cvt_pk_bf16_f32 v177, v126, v127
	v_cvt_pk_bf16_f32 v178, v112, v113
	v_cvt_pk_bf16_f32 v179, v114, v115
	s_nop 1
	v_permlane16_swap_b32_e32 v176, v178
	v_permlane16_swap_b32_e32 v177, v179
	global_store_dwordx4 v132, v[176:179], s[8:9]
	s_waitcnt vmcnt(15)
	v_permlane16_swap_b32_e32 v180, v182
	v_permlane16_swap_b32_e32 v181, v183
	s_nop 0
	v_lshlrev_b32_e32 v140, 16, v181
	v_and_b32_e32 v141, 0xffff0000, v181
	v_and_b32_e32 v181, 0xffff0000, v180
	v_lshlrev_b32_e32 v180, 16, v180
	v_lshlrev_b32_e32 v142, 16, v183
	v_and_b32_e32 v143, 0xffff0000, v183
	v_and_b32_e32 v183, 0xffff0000, v182
	v_lshlrev_b32_e32 v182, 16, v182
	v_pk_fma_f32 v[120:121], v[180:181], s[38:39], v[120:121] op_sel_hi:[1,0,1]
	v_pk_fma_f32 v[122:123], v[140:141], s[38:39], v[122:123] op_sel_hi:[1,0,1]
	v_pk_fma_f32 v[116:117], v[182:183], s[38:39], v[116:117] op_sel_hi:[1,0,1]
	v_pk_fma_f32 v[118:119], v[142:143], s[38:39], v[118:119] op_sel_hi:[1,0,1]
	v_cvt_pk_bf16_f32 v180, v120, v121
	v_cvt_pk_bf16_f32 v181, v122, v123
	v_cvt_pk_bf16_f32 v182, v116, v117
	v_cvt_pk_bf16_f32 v183, v118, v119
	s_nop 1
	v_permlane16_swap_b32_e32 v180, v182
	v_permlane16_swap_b32_e32 v181, v183
	global_store_dwordx4 v132, v[180:183], s[8:9] offset:32
	s_waitcnt vmcnt(15)
	v_permlane16_swap_b32_e32 v184, v186
	v_permlane16_swap_b32_e32 v185, v187
	s_nop 0
	v_lshlrev_b32_e32 v140, 16, v185
	v_and_b32_e32 v141, 0xffff0000, v185
	v_and_b32_e32 v185, 0xffff0000, v184
	v_lshlrev_b32_e32 v184, 16, v184
	v_lshlrev_b32_e32 v142, 16, v187
	v_and_b32_e32 v143, 0xffff0000, v187
	v_and_b32_e32 v187, 0xffff0000, v186
	v_lshlrev_b32_e32 v186, 16, v186
	v_pk_fma_f32 v[92:93], v[184:185], s[38:39], v[92:93] op_sel_hi:[1,0,1]
	v_pk_fma_f32 v[94:95], v[140:141], s[38:39], v[94:95] op_sel_hi:[1,0,1]
	v_pk_fma_f32 v[80:81], v[186:187], s[38:39], v[80:81] op_sel_hi:[1,0,1]
	v_pk_fma_f32 v[82:83], v[142:143], s[38:39], v[82:83] op_sel_hi:[1,0,1]
	v_cvt_pk_bf16_f32 v184, v92, v93
	v_cvt_pk_bf16_f32 v185, v94, v95
	v_cvt_pk_bf16_f32 v186, v80, v81
	v_cvt_pk_bf16_f32 v187, v82, v83
	s_nop 1
	v_permlane16_swap_b32_e32 v184, v186
	v_permlane16_swap_b32_e32 v185, v187
	global_store_dwordx4 v132, v[184:187], s[8:9] offset:256
	s_waitcnt vmcnt(15)
	v_permlane16_swap_b32_e32 v188, v190
	v_permlane16_swap_b32_e32 v189, v191
	s_nop 0
	v_lshlrev_b32_e32 v140, 16, v189
	v_and_b32_e32 v141, 0xffff0000, v189
	v_and_b32_e32 v189, 0xffff0000, v188
	v_lshlrev_b32_e32 v188, 16, v188
	v_lshlrev_b32_e32 v142, 16, v191
	v_and_b32_e32 v143, 0xffff0000, v191
	v_and_b32_e32 v191, 0xffff0000, v190
	v_lshlrev_b32_e32 v190, 16, v190
	v_pk_fma_f32 v[88:89], v[188:189], s[38:39], v[88:89] op_sel_hi:[1,0,1]
	v_pk_fma_f32 v[90:91], v[140:141], s[38:39], v[90:91] op_sel_hi:[1,0,1]
	v_pk_fma_f32 v[84:85], v[190:191], s[38:39], v[84:85] op_sel_hi:[1,0,1]
	v_pk_fma_f32 v[86:87], v[142:143], s[38:39], v[86:87] op_sel_hi:[1,0,1]
	v_cvt_pk_bf16_f32 v188, v88, v89
	v_cvt_pk_bf16_f32 v189, v90, v91
	v_cvt_pk_bf16_f32 v190, v84, v85
	v_cvt_pk_bf16_f32 v191, v86, v87
	s_nop 1
	v_permlane16_swap_b32_e32 v188, v190
	v_permlane16_swap_b32_e32 v189, v191
	global_store_dwordx4 v132, v[188:191], s[8:9] offset:288
	s_waitcnt vmcnt(15)
	v_permlane16_swap_b32_e32 v192, v194
	v_permlane16_swap_b32_e32 v193, v195
	s_nop 0
	v_lshlrev_b32_e32 v140, 16, v193
	v_and_b32_e32 v141, 0xffff0000, v193
	v_and_b32_e32 v193, 0xffff0000, v192
	v_lshlrev_b32_e32 v192, 16, v192
	v_lshlrev_b32_e32 v142, 16, v195
	v_and_b32_e32 v143, 0xffff0000, v195
	v_and_b32_e32 v195, 0xffff0000, v194
	v_lshlrev_b32_e32 v194, 16, v194
	v_pk_fma_f32 v[104:105], v[192:193], s[38:39], v[104:105] op_sel_hi:[1,0,1]
	v_pk_fma_f32 v[106:107], v[140:141], s[38:39], v[106:107] op_sel_hi:[1,0,1]
	v_pk_fma_f32 v[96:97], v[194:195], s[38:39], v[96:97] op_sel_hi:[1,0,1]
	v_pk_fma_f32 v[98:99], v[142:143], s[38:39], v[98:99] op_sel_hi:[1,0,1]
	v_cvt_pk_bf16_f32 v192, v104, v105
	v_cvt_pk_bf16_f32 v193, v106, v107
	v_cvt_pk_bf16_f32 v194, v96, v97
	v_cvt_pk_bf16_f32 v195, v98, v99
	s_nop 1
	v_permlane16_swap_b32_e32 v192, v194
	v_permlane16_swap_b32_e32 v193, v195
	global_store_dwordx4 v134, v[192:195], s[8:9]
	s_waitcnt vmcnt(15)
	v_permlane16_swap_b32_e32 v196, v198
	v_permlane16_swap_b32_e32 v197, v199
	s_nop 0
	v_lshlrev_b32_e32 v140, 16, v197
	v_and_b32_e32 v141, 0xffff0000, v197
	v_and_b32_e32 v197, 0xffff0000, v196
	v_lshlrev_b32_e32 v196, 16, v196
	v_lshlrev_b32_e32 v142, 16, v199
	v_and_b32_e32 v143, 0xffff0000, v199
	v_and_b32_e32 v199, 0xffff0000, v198
	v_lshlrev_b32_e32 v198, 16, v198
	v_pk_fma_f32 v[108:109], v[196:197], s[38:39], v[108:109] op_sel_hi:[1,0,1]
	v_pk_fma_f32 v[110:111], v[140:141], s[38:39], v[110:111] op_sel_hi:[1,0,1]
	v_pk_fma_f32 v[100:101], v[198:199], s[38:39], v[100:101] op_sel_hi:[1,0,1]
	v_pk_fma_f32 v[102:103], v[142:143], s[38:39], v[102:103] op_sel_hi:[1,0,1]
	v_cvt_pk_bf16_f32 v196, v108, v109
	v_cvt_pk_bf16_f32 v197, v110, v111
	v_cvt_pk_bf16_f32 v198, v100, v101
	v_cvt_pk_bf16_f32 v199, v102, v103
	s_nop 1
	v_permlane16_swap_b32_e32 v196, v198
	v_permlane16_swap_b32_e32 v197, v199
	global_store_dwordx4 v134, v[196:199], s[8:9] offset:32
	s_waitcnt vmcnt(15)
	v_permlane16_swap_b32_e32 v200, v202
	v_permlane16_swap_b32_e32 v201, v203
	s_nop 0
	v_lshlrev_b32_e32 v140, 16, v201
	v_and_b32_e32 v141, 0xffff0000, v201
	v_and_b32_e32 v201, 0xffff0000, v200
	v_lshlrev_b32_e32 v200, 16, v200
	v_lshlrev_b32_e32 v142, 16, v203
	v_and_b32_e32 v143, 0xffff0000, v203
	v_and_b32_e32 v203, 0xffff0000, v202
	v_lshlrev_b32_e32 v202, 16, v202
	v_pk_fma_f32 v[72:73], v[200:201], s[38:39], v[72:73] op_sel_hi:[1,0,1]
	v_pk_fma_f32 v[74:75], v[140:141], s[38:39], v[74:75] op_sel_hi:[1,0,1]
	v_pk_fma_f32 v[64:65], v[202:203], s[38:39], v[64:65] op_sel_hi:[1,0,1]
	v_pk_fma_f32 v[66:67], v[142:143], s[38:39], v[66:67] op_sel_hi:[1,0,1]
	v_cvt_pk_bf16_f32 v200, v72, v73
	v_cvt_pk_bf16_f32 v201, v74, v75
	v_cvt_pk_bf16_f32 v202, v64, v65
	v_cvt_pk_bf16_f32 v203, v66, v67
	s_nop 1
	v_permlane16_swap_b32_e32 v200, v202
	v_permlane16_swap_b32_e32 v201, v203
	global_store_dwordx4 v134, v[200:203], s[8:9] offset:256
	s_waitcnt vmcnt(15)
	v_permlane16_swap_b32_e32 v204, v206
	v_permlane16_swap_b32_e32 v205, v207
	s_nop 0
	v_lshlrev_b32_e32 v140, 16, v205
	v_and_b32_e32 v141, 0xffff0000, v205
	v_and_b32_e32 v205, 0xffff0000, v204
	v_lshlrev_b32_e32 v204, 16, v204
	v_lshlrev_b32_e32 v142, 16, v207
	v_and_b32_e32 v143, 0xffff0000, v207
	v_and_b32_e32 v207, 0xffff0000, v206
	v_lshlrev_b32_e32 v206, 16, v206
	v_pk_fma_f32 v[76:77], v[204:205], s[38:39], v[76:77] op_sel_hi:[1,0,1]
	v_pk_fma_f32 v[78:79], v[140:141], s[38:39], v[78:79] op_sel_hi:[1,0,1]
	v_pk_fma_f32 v[68:69], v[206:207], s[38:39], v[68:69] op_sel_hi:[1,0,1]
	v_pk_fma_f32 v[70:71], v[142:143], s[38:39], v[70:71] op_sel_hi:[1,0,1]
	v_cvt_pk_bf16_f32 v204, v76, v77
	v_cvt_pk_bf16_f32 v205, v78, v79
	v_cvt_pk_bf16_f32 v206, v68, v69
	v_cvt_pk_bf16_f32 v207, v70, v71
	s_nop 1
	v_permlane16_swap_b32_e32 v204, v206
	v_permlane16_swap_b32_e32 v205, v207
	global_store_dwordx4 v134, v[204:207], s[8:9] offset:288
	s_waitcnt vmcnt(15)
	v_permlane16_swap_b32_e32 v208, v210
	v_permlane16_swap_b32_e32 v209, v211
	s_nop 0
	v_lshlrev_b32_e32 v140, 16, v209
	v_and_b32_e32 v141, 0xffff0000, v209
	v_and_b32_e32 v209, 0xffff0000, v208
	v_lshlrev_b32_e32 v208, 16, v208
	v_lshlrev_b32_e32 v142, 16, v211
	v_and_b32_e32 v143, 0xffff0000, v211
	v_and_b32_e32 v211, 0xffff0000, v210
	v_lshlrev_b32_e32 v210, 16, v210
	v_pk_fma_f32 v[60:61], v[208:209], s[38:39], v[60:61] op_sel_hi:[1,0,1]
	v_pk_fma_f32 v[62:63], v[140:141], s[38:39], v[62:63] op_sel_hi:[1,0,1]
	v_pk_fma_f32 v[48:49], v[210:211], s[38:39], v[48:49] op_sel_hi:[1,0,1]
	v_pk_fma_f32 v[50:51], v[142:143], s[38:39], v[50:51] op_sel_hi:[1,0,1]
	v_cvt_pk_bf16_f32 v208, v60, v61
	v_cvt_pk_bf16_f32 v209, v62, v63
	v_cvt_pk_bf16_f32 v210, v48, v49
	v_cvt_pk_bf16_f32 v211, v50, v51
	s_nop 1
	v_permlane16_swap_b32_e32 v208, v210
	v_permlane16_swap_b32_e32 v209, v211
	global_store_dwordx4 v136, v[208:211], s[8:9]
	s_waitcnt vmcnt(15)
	v_permlane16_swap_b32_e32 v212, v214
	v_permlane16_swap_b32_e32 v213, v215
	s_nop 0
	v_lshlrev_b32_e32 v140, 16, v213
	v_and_b32_e32 v141, 0xffff0000, v213
	v_and_b32_e32 v213, 0xffff0000, v212
	v_lshlrev_b32_e32 v212, 16, v212
	v_lshlrev_b32_e32 v142, 16, v215
	v_and_b32_e32 v143, 0xffff0000, v215
	v_and_b32_e32 v215, 0xffff0000, v214
	v_lshlrev_b32_e32 v214, 16, v214
	v_pk_fma_f32 v[56:57], v[212:213], s[38:39], v[56:57] op_sel_hi:[1,0,1]
	v_pk_fma_f32 v[58:59], v[140:141], s[38:39], v[58:59] op_sel_hi:[1,0,1]
	v_pk_fma_f32 v[52:53], v[214:215], s[38:39], v[52:53] op_sel_hi:[1,0,1]
	v_pk_fma_f32 v[54:55], v[142:143], s[38:39], v[54:55] op_sel_hi:[1,0,1]
	v_cvt_pk_bf16_f32 v212, v56, v57
	v_cvt_pk_bf16_f32 v213, v58, v59
	v_cvt_pk_bf16_f32 v214, v52, v53
	v_cvt_pk_bf16_f32 v215, v54, v55
	s_nop 1
	v_permlane16_swap_b32_e32 v212, v214
	v_permlane16_swap_b32_e32 v213, v215
	global_store_dwordx4 v136, v[212:215], s[8:9] offset:32
	s_waitcnt vmcnt(15)
	v_permlane16_swap_b32_e32 v216, v218
	v_permlane16_swap_b32_e32 v217, v219
	s_nop 0
	v_lshlrev_b32_e32 v140, 16, v217
	v_and_b32_e32 v141, 0xffff0000, v217
	v_and_b32_e32 v217, 0xffff0000, v216
	v_lshlrev_b32_e32 v216, 16, v216
	v_lshlrev_b32_e32 v142, 16, v219
	v_and_b32_e32 v143, 0xffff0000, v219
	v_and_b32_e32 v219, 0xffff0000, v218
	v_lshlrev_b32_e32 v218, 16, v218
	v_pk_fma_f32 v[28:29], v[216:217], s[38:39], v[28:29] op_sel_hi:[1,0,1]
	v_pk_fma_f32 v[30:31], v[140:141], s[38:39], v[30:31] op_sel_hi:[1,0,1]
	v_pk_fma_f32 v[16:17], v[218:219], s[38:39], v[16:17] op_sel_hi:[1,0,1]
	v_pk_fma_f32 v[18:19], v[142:143], s[38:39], v[18:19] op_sel_hi:[1,0,1]
	v_cvt_pk_bf16_f32 v216, v28, v29
	v_cvt_pk_bf16_f32 v217, v30, v31
	v_cvt_pk_bf16_f32 v218, v16, v17
	v_cvt_pk_bf16_f32 v219, v18, v19
	s_nop 1
	v_permlane16_swap_b32_e32 v216, v218
	v_permlane16_swap_b32_e32 v217, v219
	global_store_dwordx4 v136, v[216:219], s[8:9] offset:256
	s_waitcnt vmcnt(15)
	v_permlane16_swap_b32_e32 v220, v222
	v_permlane16_swap_b32_e32 v221, v223
	s_nop 0
	v_lshlrev_b32_e32 v140, 16, v221
	v_and_b32_e32 v141, 0xffff0000, v221
	v_and_b32_e32 v221, 0xffff0000, v220
	v_lshlrev_b32_e32 v220, 16, v220
	v_lshlrev_b32_e32 v142, 16, v223
	v_and_b32_e32 v143, 0xffff0000, v223
	v_and_b32_e32 v223, 0xffff0000, v222
	v_lshlrev_b32_e32 v222, 16, v222
	v_pk_fma_f32 v[24:25], v[220:221], s[38:39], v[24:25] op_sel_hi:[1,0,1]
	v_pk_fma_f32 v[26:27], v[140:141], s[38:39], v[26:27] op_sel_hi:[1,0,1]
	v_pk_fma_f32 v[20:21], v[222:223], s[38:39], v[20:21] op_sel_hi:[1,0,1]
	v_pk_fma_f32 v[22:23], v[142:143], s[38:39], v[22:23] op_sel_hi:[1,0,1]
	v_cvt_pk_bf16_f32 v220, v24, v25
	v_cvt_pk_bf16_f32 v221, v26, v27
	v_cvt_pk_bf16_f32 v222, v20, v21
	v_cvt_pk_bf16_f32 v223, v22, v23
	s_nop 1
	v_permlane16_swap_b32_e32 v220, v222
	v_permlane16_swap_b32_e32 v221, v223
	global_store_dwordx4 v136, v[220:223], s[8:9] offset:288
	s_waitcnt vmcnt(15)
	v_permlane16_swap_b32_e32 v224, v226
	v_permlane16_swap_b32_e32 v225, v227
	s_nop 0
	v_lshlrev_b32_e32 v140, 16, v225
	v_and_b32_e32 v141, 0xffff0000, v225
	v_and_b32_e32 v225, 0xffff0000, v224
	v_lshlrev_b32_e32 v224, 16, v224
	v_lshlrev_b32_e32 v142, 16, v227
	v_and_b32_e32 v143, 0xffff0000, v227
	v_and_b32_e32 v227, 0xffff0000, v226
	v_lshlrev_b32_e32 v226, 16, v226
	v_pk_fma_f32 v[40:41], v[224:225], s[38:39], v[40:41] op_sel_hi:[1,0,1]
	v_pk_fma_f32 v[42:43], v[140:141], s[38:39], v[42:43] op_sel_hi:[1,0,1]
	v_pk_fma_f32 v[32:33], v[226:227], s[38:39], v[32:33] op_sel_hi:[1,0,1]
	v_pk_fma_f32 v[34:35], v[142:143], s[38:39], v[34:35] op_sel_hi:[1,0,1]
	v_cvt_pk_bf16_f32 v224, v40, v41
	v_cvt_pk_bf16_f32 v225, v42, v43
	v_cvt_pk_bf16_f32 v226, v32, v33
	v_cvt_pk_bf16_f32 v227, v34, v35
	s_nop 1
	v_permlane16_swap_b32_e32 v224, v226
	v_permlane16_swap_b32_e32 v225, v227
	global_store_dwordx4 v138, v[224:227], s[8:9]
	s_waitcnt vmcnt(15)
	v_permlane16_swap_b32_e32 v228, v230
	v_permlane16_swap_b32_e32 v229, v231
	s_nop 0
	v_lshlrev_b32_e32 v140, 16, v229
	v_and_b32_e32 v141, 0xffff0000, v229
	v_and_b32_e32 v229, 0xffff0000, v228
	v_lshlrev_b32_e32 v228, 16, v228
	v_lshlrev_b32_e32 v142, 16, v231
	v_and_b32_e32 v143, 0xffff0000, v231
	v_and_b32_e32 v231, 0xffff0000, v230
	v_lshlrev_b32_e32 v230, 16, v230
	v_pk_fma_f32 v[44:45], v[228:229], s[38:39], v[44:45] op_sel_hi:[1,0,1]
	v_pk_fma_f32 v[46:47], v[140:141], s[38:39], v[46:47] op_sel_hi:[1,0,1]
	v_pk_fma_f32 v[36:37], v[230:231], s[38:39], v[36:37] op_sel_hi:[1,0,1]
	v_pk_fma_f32 v[38:39], v[142:143], s[38:39], v[38:39] op_sel_hi:[1,0,1]
	v_cvt_pk_bf16_f32 v228, v44, v45
	v_cvt_pk_bf16_f32 v229, v46, v47
	v_cvt_pk_bf16_f32 v230, v36, v37
	v_cvt_pk_bf16_f32 v231, v38, v39
	s_nop 1
	v_permlane16_swap_b32_e32 v228, v230
	v_permlane16_swap_b32_e32 v229, v231
	global_store_dwordx4 v138, v[228:231], s[8:9] offset:32
	s_waitcnt vmcnt(15)
	v_permlane16_swap_b32_e32 v232, v234
	v_permlane16_swap_b32_e32 v233, v235
	s_nop 0
	v_lshlrev_b32_e32 v140, 16, v233
	v_and_b32_e32 v141, 0xffff0000, v233
	v_and_b32_e32 v233, 0xffff0000, v232
	v_lshlrev_b32_e32 v232, 16, v232
	v_lshlrev_b32_e32 v142, 16, v235
	v_and_b32_e32 v143, 0xffff0000, v235
	v_and_b32_e32 v235, 0xffff0000, v234
	v_lshlrev_b32_e32 v234, 16, v234
	v_pk_fma_f32 v[8:9], v[232:233], s[38:39], v[8:9] op_sel_hi:[1,0,1]
	v_pk_fma_f32 v[10:11], v[140:141], s[38:39], v[10:11] op_sel_hi:[1,0,1]
	v_pk_fma_f32 v[0:1], v[234:235], s[38:39], v[0:1] op_sel_hi:[1,0,1]
	v_pk_fma_f32 v[2:3], v[142:143], s[38:39], v[2:3] op_sel_hi:[1,0,1]
	v_cvt_pk_bf16_f32 v232, v8, v9
	v_cvt_pk_bf16_f32 v233, v10, v11
	v_cvt_pk_bf16_f32 v234, v0, v1
	v_cvt_pk_bf16_f32 v235, v2, v3
	s_nop 1
	v_permlane16_swap_b32_e32 v232, v234
	v_permlane16_swap_b32_e32 v233, v235
	global_store_dwordx4 v138, v[232:235], s[8:9] offset:256
	s_waitcnt vmcnt(15)
	v_permlane16_swap_b32_e32 v236, v238
	v_permlane16_swap_b32_e32 v237, v239
	s_nop 0
	v_lshlrev_b32_e32 v140, 16, v237
	v_and_b32_e32 v141, 0xffff0000, v237
	v_and_b32_e32 v237, 0xffff0000, v236
	v_lshlrev_b32_e32 v236, 16, v236
	v_lshlrev_b32_e32 v142, 16, v239
	v_and_b32_e32 v143, 0xffff0000, v239
	v_and_b32_e32 v239, 0xffff0000, v238
	v_lshlrev_b32_e32 v238, 16, v238
	v_pk_fma_f32 v[12:13], v[236:237], s[38:39], v[12:13] op_sel_hi:[1,0,1]
	v_pk_fma_f32 v[14:15], v[140:141], s[38:39], v[14:15] op_sel_hi:[1,0,1]
	v_pk_fma_f32 v[4:5], v[238:239], s[38:39], v[4:5] op_sel_hi:[1,0,1]
	v_pk_fma_f32 v[6:7], v[142:143], s[38:39], v[6:7] op_sel_hi:[1,0,1]
	v_cvt_pk_bf16_f32 v236, v12, v13
	v_cvt_pk_bf16_f32 v237, v14, v15
	v_cvt_pk_bf16_f32 v238, v4, v5
	v_cvt_pk_bf16_f32 v239, v6, v7
	s_nop 1
	v_permlane16_swap_b32_e32 v236, v238
	v_permlane16_swap_b32_e32 v237, v239
	global_store_dwordx4 v138, v[236:239], s[8:9] offset:288
	s_andn2_b64 vcc, exec, s[0:1]
	s_mov_b32 s43, s61
	s_mov_b32 s42, s62
	s_cbranch_vccz .LBB0_577

.LBB0_749:
	s_or_b64 exec, exec, s[38:39]
	s_lshl_b32 s98, s61, 1
	s_lshl_b32 s99, s62, 11
	s_add_i32 s98, s98, s99
	v_lshlrev_b32_e32 v132, 6, v150
	v_lshl_add_u32 v132, v151, 3, v132
	v_lshl_add_u32 v132, v152, 11, v132
	v_lshl_add_u32 v132, v149, 17, v132
	v_add_u32_e32 v132, s98, v132
	v_add_u32_e32 v133, 0x8000, v132
	v_add_u32_e32 v134, 0x10000, v132
	v_add_u32_e32 v135, 0x18000, v132
	v_add_u32_e32 v136, 0x40000, v132
	v_add_u32_e32 v137, 0x48000, v132
	v_add_u32_e32 v138, 0x50000, v132
	v_add_u32_e32 v139, 0x58000, v132
	v_bfe_u32 v133, v154, 4, 1
	v_mul_u32_u24_e32 v133, 0x7ff8, v133
	v_add_u32_e32 v132, v132, v133
	v_add_u32_e32 v134, v134, v133
	v_add_u32_e32 v136, v136, v133
	v_add_u32_e32 v138, v138, v133
	global_load_dwordx4 v[180:183], v132, s[8:9]
	global_load_dwordx4 v[184:187], v132, s[8:9] offset:32
	global_load_dwordx4 v[188:191], v132, s[8:9] offset:256
	global_load_dwordx4 v[192:195], v132, s[8:9] offset:288
	global_load_dwordx4 v[196:199], v134, s[8:9]
	global_load_dwordx4 v[200:203], v134, s[8:9] offset:32
	global_load_dwordx4 v[204:207], v134, s[8:9] offset:256
	global_load_dwordx4 v[208:211], v134, s[8:9] offset:288
	global_load_dwordx4 v[212:215], v136, s[8:9]
	global_load_dwordx4 v[216:219], v136, s[8:9] offset:32
	global_load_dwordx4 v[220:223], v136, s[8:9] offset:256
	global_load_dwordx4 v[224:227], v136, s[8:9] offset:288
	global_load_dwordx4 v[228:231], v138, s[8:9]
	global_load_dwordx4 v[232:235], v138, s[8:9] offset:32
	global_load_dwordx4 v[236:239], v138, s[8:9] offset:256
	global_load_dwordx4 v[240:243], v138, s[8:9] offset:288
	s_waitcnt vmcnt(15)
	v_permlane16_swap_b32_e32 v180, v182
	v_permlane16_swap_b32_e32 v181, v183
	s_nop 0
	v_lshlrev_b32_e32 v140, 16, v181
	v_and_b32_e32 v141, 0xffff0000, v181
	v_and_b32_e32 v181, 0xffff0000, v180
	v_lshlrev_b32_e32 v180, 16, v180
	v_lshlrev_b32_e32 v142, 16, v183
	v_and_b32_e32 v143, 0xffff0000, v183
	v_and_b32_e32 v183, 0xffff0000, v182
	v_lshlrev_b32_e32 v182, 16, v182
	v_pk_fma_f32 v[124:125], v[180:181], s[30:31], v[124:125] op_sel_hi:[1,0,1]
	v_pk_fma_f32 v[126:127], v[140:141], s[30:31], v[126:127] op_sel_hi:[1,0,1]
	v_pk_fma_f32 v[112:113], v[182:183], s[30:31], v[112:113] op_sel_hi:[1,0,1]
	v_pk_fma_f32 v[114:115], v[142:143], s[30:31], v[114:115] op_sel_hi:[1,0,1]
	v_cvt_pk_bf16_f32 v180, v124, v125
	v_cvt_pk_bf16_f32 v181, v126, v127
	v_cvt_pk_bf16_f32 v182, v112, v113
	v_cvt_pk_bf16_f32 v183, v114, v115
	s_nop 1
	v_permlane16_swap_b32_e32 v180, v182
	v_permlane16_swap_b32_e32 v181, v183
	global_store_dwordx4 v132, v[180:183], s[6:7]
	s_waitcnt vmcnt(15)
	v_permlane16_swap_b32_e32 v184, v186
	v_permlane16_swap_b32_e32 v185, v187
	s_nop 0
	v_lshlrev_b32_e32 v140, 16, v185
	v_and_b32_e32 v141, 0xffff0000, v185
	v_and_b32_e32 v185, 0xffff0000, v184
	v_lshlrev_b32_e32 v184, 16, v184
	v_lshlrev_b32_e32 v142, 16, v187
	v_and_b32_e32 v143, 0xffff0000, v187
	v_and_b32_e32 v187, 0xffff0000, v186
	v_lshlrev_b32_e32 v186, 16, v186
	v_pk_fma_f32 v[120:121], v[184:185], s[30:31], v[120:121] op_sel_hi:[1,0,1]
	v_pk_fma_f32 v[122:123], v[140:141], s[30:31], v[122:123] op_sel_hi:[1,0,1]
	v_pk_fma_f32 v[116:117], v[186:187], s[30:31], v[116:117] op_sel_hi:[1,0,1]
	v_pk_fma_f32 v[118:119], v[142:143], s[30:31], v[118:119] op_sel_hi:[1,0,1]
	v_cvt_pk_bf16_f32 v184, v120, v121
	v_cvt_pk_bf16_f32 v185, v122, v123
	v_cvt_pk_bf16_f32 v186, v116, v117
	v_cvt_pk_bf16_f32 v187, v118, v119
	s_nop 1
	v_permlane16_swap_b32_e32 v184, v186
	v_permlane16_swap_b32_e32 v185, v187
	global_store_dwordx4 v132, v[184:187], s[6:7] offset:32
	s_waitcnt vmcnt(15)
	v_permlane16_swap_b32_e32 v188, v190
	v_permlane16_swap_b32_e32 v189, v191
	s_nop 0
	v_lshlrev_b32_e32 v140, 16, v189
	v_and_b32_e32 v141, 0xffff0000, v189
	v_and_b32_e32 v189, 0xffff0000, v188
	v_lshlrev_b32_e32 v188, 16, v188
	v_lshlrev_b32_e32 v142, 16, v191
	v_and_b32_e32 v143, 0xffff0000, v191
	v_and_b32_e32 v191, 0xffff0000, v190
	v_lshlrev_b32_e32 v190, 16, v190
	v_pk_fma_f32 v[92:93], v[188:189], s[30:31], v[92:93] op_sel_hi:[1,0,1]
	v_pk_fma_f32 v[94:95], v[140:141], s[30:31], v[94:95] op_sel_hi:[1,0,1]
	v_pk_fma_f32 v[80:81], v[190:191], s[30:31], v[80:81] op_sel_hi:[1,0,1]
	v_pk_fma_f32 v[82:83], v[142:143], s[30:31], v[82:83] op_sel_hi:[1,0,1]
	v_cvt_pk_bf16_f32 v188, v92, v93
	v_cvt_pk_bf16_f32 v189, v94, v95
	v_cvt_pk_bf16_f32 v190, v80, v81
	v_cvt_pk_bf16_f32 v191, v82, v83
	s_nop 1
	v_permlane16_swap_b32_e32 v188, v190
	v_permlane16_swap_b32_e32 v189, v191
	global_store_dwordx4 v132, v[188:191], s[6:7] offset:256
	s_waitcnt vmcnt(15)
	v_permlane16_swap_b32_e32 v192, v194
	v_permlane16_swap_b32_e32 v193, v195
	s_nop 0
	v_lshlrev_b32_e32 v140, 16, v193
	v_and_b32_e32 v141, 0xffff0000, v193
	v_and_b32_e32 v193, 0xffff0000, v192
	v_lshlrev_b32_e32 v192, 16, v192
	v_lshlrev_b32_e32 v142, 16, v195
	v_and_b32_e32 v143, 0xffff0000, v195
	v_and_b32_e32 v195, 0xffff0000, v194
	v_lshlrev_b32_e32 v194, 16, v194
	v_pk_fma_f32 v[88:89], v[192:193], s[30:31], v[88:89] op_sel_hi:[1,0,1]
	v_pk_fma_f32 v[90:91], v[140:141], s[30:31], v[90:91] op_sel_hi:[1,0,1]
	v_pk_fma_f32 v[84:85], v[194:195], s[30:31], v[84:85] op_sel_hi:[1,0,1]
	v_pk_fma_f32 v[86:87], v[142:143], s[30:31], v[86:87] op_sel_hi:[1,0,1]
	v_cvt_pk_bf16_f32 v192, v88, v89
	v_cvt_pk_bf16_f32 v193, v90, v91
	v_cvt_pk_bf16_f32 v194, v84, v85
	v_cvt_pk_bf16_f32 v195, v86, v87
	s_nop 1
	v_permlane16_swap_b32_e32 v192, v194
	v_permlane16_swap_b32_e32 v193, v195
	global_store_dwordx4 v132, v[192:195], s[6:7] offset:288
	s_waitcnt vmcnt(15)
	v_permlane16_swap_b32_e32 v196, v198
	v_permlane16_swap_b32_e32 v197, v199
	s_nop 0
	v_lshlrev_b32_e32 v140, 16, v197
	v_and_b32_e32 v141, 0xffff0000, v197
	v_and_b32_e32 v197, 0xffff0000, v196
	v_lshlrev_b32_e32 v196, 16, v196
	v_lshlrev_b32_e32 v142, 16, v199
	v_and_b32_e32 v143, 0xffff0000, v199
	v_and_b32_e32 v199, 0xffff0000, v198
	v_lshlrev_b32_e32 v198, 16, v198
	v_pk_fma_f32 v[104:105], v[196:197], s[30:31], v[104:105] op_sel_hi:[1,0,1]
	v_pk_fma_f32 v[106:107], v[140:141], s[30:31], v[106:107] op_sel_hi:[1,0,1]
	v_pk_fma_f32 v[96:97], v[198:199], s[30:31], v[96:97] op_sel_hi:[1,0,1]
	v_pk_fma_f32 v[98:99], v[142:143], s[30:31], v[98:99] op_sel_hi:[1,0,1]
	v_cvt_pk_bf16_f32 v196, v104, v105
	v_cvt_pk_bf16_f32 v197, v106, v107
	v_cvt_pk_bf16_f32 v198, v96, v97
	v_cvt_pk_bf16_f32 v199, v98, v99
	s_nop 1
	v_permlane16_swap_b32_e32 v196, v198
	v_permlane16_swap_b32_e32 v197, v199
	global_store_dwordx4 v134, v[196:199], s[6:7]
	s_waitcnt vmcnt(15)
	v_permlane16_swap_b32_e32 v200, v202
	v_permlane16_swap_b32_e32 v201, v203
	s_nop 0
	v_lshlrev_b32_e32 v140, 16, v201
	v_and_b32_e32 v141, 0xffff0000, v201
	v_and_b32_e32 v201, 0xffff0000, v200
	v_lshlrev_b32_e32 v200, 16, v200
	v_lshlrev_b32_e32 v142, 16, v203
	v_and_b32_e32 v143, 0xffff0000, v203
	v_and_b32_e32 v203, 0xffff0000, v202
	v_lshlrev_b32_e32 v202, 16, v202
	v_pk_fma_f32 v[108:109], v[200:201], s[30:31], v[108:109] op_sel_hi:[1,0,1]
	v_pk_fma_f32 v[110:111], v[140:141], s[30:31], v[110:111] op_sel_hi:[1,0,1]
	v_pk_fma_f32 v[100:101], v[202:203], s[30:31], v[100:101] op_sel_hi:[1,0,1]
	v_pk_fma_f32 v[102:103], v[142:143], s[30:31], v[102:103] op_sel_hi:[1,0,1]
	v_cvt_pk_bf16_f32 v200, v108, v109
	v_cvt_pk_bf16_f32 v201, v110, v111
	v_cvt_pk_bf16_f32 v202, v100, v101
	v_cvt_pk_bf16_f32 v203, v102, v103
	s_nop 1
	v_permlane16_swap_b32_e32 v200, v202
	v_permlane16_swap_b32_e32 v201, v203
	global_store_dwordx4 v134, v[200:203], s[6:7] offset:32
	s_waitcnt vmcnt(15)
	v_permlane16_swap_b32_e32 v204, v206
	v_permlane16_swap_b32_e32 v205, v207
	s_nop 0
	v_lshlrev_b32_e32 v140, 16, v205
	v_and_b32_e32 v141, 0xffff0000, v205
	v_and_b32_e32 v205, 0xffff0000, v204
	v_lshlrev_b32_e32 v204, 16, v204
	v_lshlrev_b32_e32 v142, 16, v207
	v_and_b32_e32 v143, 0xffff0000, v207
	v_and_b32_e32 v207, 0xffff0000, v206
	v_lshlrev_b32_e32 v206, 16, v206
	v_pk_fma_f32 v[72:73], v[204:205], s[30:31], v[72:73] op_sel_hi:[1,0,1]
	v_pk_fma_f32 v[74:75], v[140:141], s[30:31], v[74:75] op_sel_hi:[1,0,1]
	v_pk_fma_f32 v[64:65], v[206:207], s[30:31], v[64:65] op_sel_hi:[1,0,1]
	v_pk_fma_f32 v[66:67], v[142:143], s[30:31], v[66:67] op_sel_hi:[1,0,1]
	v_cvt_pk_bf16_f32 v204, v72, v73
	v_cvt_pk_bf16_f32 v205, v74, v75
	v_cvt_pk_bf16_f32 v206, v64, v65
	v_cvt_pk_bf16_f32 v207, v66, v67
	s_nop 1
	v_permlane16_swap_b32_e32 v204, v206
	v_permlane16_swap_b32_e32 v205, v207
	global_store_dwordx4 v134, v[204:207], s[6:7] offset:256
	s_waitcnt vmcnt(15)
	v_permlane16_swap_b32_e32 v208, v210
	v_permlane16_swap_b32_e32 v209, v211
	s_nop 0
	v_lshlrev_b32_e32 v140, 16, v209
	v_and_b32_e32 v141, 0xffff0000, v209
	v_and_b32_e32 v209, 0xffff0000, v208
	v_lshlrev_b32_e32 v208, 16, v208
	v_lshlrev_b32_e32 v142, 16, v211
	v_and_b32_e32 v143, 0xffff0000, v211
	v_and_b32_e32 v211, 0xffff0000, v210
	v_lshlrev_b32_e32 v210, 16, v210
	v_pk_fma_f32 v[76:77], v[208:209], s[30:31], v[76:77] op_sel_hi:[1,0,1]
	v_pk_fma_f32 v[78:79], v[140:141], s[30:31], v[78:79] op_sel_hi:[1,0,1]
	v_pk_fma_f32 v[68:69], v[210:211], s[30:31], v[68:69] op_sel_hi:[1,0,1]
	v_pk_fma_f32 v[70:71], v[142:143], s[30:31], v[70:71] op_sel_hi:[1,0,1]
	v_cvt_pk_bf16_f32 v208, v76, v77
	v_cvt_pk_bf16_f32 v209, v78, v79
	v_cvt_pk_bf16_f32 v210, v68, v69
	v_cvt_pk_bf16_f32 v211, v70, v71
	s_nop 1
	v_permlane16_swap_b32_e32 v208, v210
	v_permlane16_swap_b32_e32 v209, v211
	global_store_dwordx4 v134, v[208:211], s[6:7] offset:288
	s_waitcnt vmcnt(15)
	v_permlane16_swap_b32_e32 v212, v214
	v_permlane16_swap_b32_e32 v213, v215
	s_nop 0
	v_lshlrev_b32_e32 v140, 16, v213
	v_and_b32_e32 v141, 0xffff0000, v213
	v_and_b32_e32 v213, 0xffff0000, v212
	v_lshlrev_b32_e32 v212, 16, v212
	v_lshlrev_b32_e32 v142, 16, v215
	v_and_b32_e32 v143, 0xffff0000, v215
	v_and_b32_e32 v215, 0xffff0000, v214
	v_lshlrev_b32_e32 v214, 16, v214
	v_pk_fma_f32 v[60:61], v[212:213], s[30:31], v[60:61] op_sel_hi:[1,0,1]
	v_pk_fma_f32 v[62:63], v[140:141], s[30:31], v[62:63] op_sel_hi:[1,0,1]
	v_pk_fma_f32 v[48:49], v[214:215], s[30:31], v[48:49] op_sel_hi:[1,0,1]
	v_pk_fma_f32 v[50:51], v[142:143], s[30:31], v[50:51] op_sel_hi:[1,0,1]
	v_cvt_pk_bf16_f32 v212, v60, v61
	v_cvt_pk_bf16_f32 v213, v62, v63
	v_cvt_pk_bf16_f32 v214, v48, v49
	v_cvt_pk_bf16_f32 v215, v50, v51
	s_nop 1
	v_permlane16_swap_b32_e32 v212, v214
	v_permlane16_swap_b32_e32 v213, v215
	global_store_dwordx4 v136, v[212:215], s[6:7]
	s_waitcnt vmcnt(15)
	v_permlane16_swap_b32_e32 v216, v218
	v_permlane16_swap_b32_e32 v217, v219
	s_nop 0
	v_lshlrev_b32_e32 v140, 16, v217
	v_and_b32_e32 v141, 0xffff0000, v217
	v_and_b32_e32 v217, 0xffff0000, v216
	v_lshlrev_b32_e32 v216, 16, v216
	v_lshlrev_b32_e32 v142, 16, v219
	v_and_b32_e32 v143, 0xffff0000, v219
	v_and_b32_e32 v219, 0xffff0000, v218
	v_lshlrev_b32_e32 v218, 16, v218
	v_pk_fma_f32 v[56:57], v[216:217], s[30:31], v[56:57] op_sel_hi:[1,0,1]
	v_pk_fma_f32 v[58:59], v[140:141], s[30:31], v[58:59] op_sel_hi:[1,0,1]
	v_pk_fma_f32 v[52:53], v[218:219], s[30:31], v[52:53] op_sel_hi:[1,0,1]
	v_pk_fma_f32 v[54:55], v[142:143], s[30:31], v[54:55] op_sel_hi:[1,0,1]
	v_cvt_pk_bf16_f32 v216, v56, v57
	v_cvt_pk_bf16_f32 v217, v58, v59
	v_cvt_pk_bf16_f32 v218, v52, v53
	v_cvt_pk_bf16_f32 v219, v54, v55
	s_nop 1
	v_permlane16_swap_b32_e32 v216, v218
	v_permlane16_swap_b32_e32 v217, v219
	global_store_dwordx4 v136, v[216:219], s[6:7] offset:32
	s_waitcnt vmcnt(15)
	v_permlane16_swap_b32_e32 v220, v222
	v_permlane16_swap_b32_e32 v221, v223
	s_nop 0
	v_lshlrev_b32_e32 v140, 16, v221
	v_and_b32_e32 v141, 0xffff0000, v221
	v_and_b32_e32 v221, 0xffff0000, v220
	v_lshlrev_b32_e32 v220, 16, v220
	v_lshlrev_b32_e32 v142, 16, v223
	v_and_b32_e32 v143, 0xffff0000, v223
	v_and_b32_e32 v223, 0xffff0000, v222
	v_lshlrev_b32_e32 v222, 16, v222
	v_pk_fma_f32 v[28:29], v[220:221], s[30:31], v[28:29] op_sel_hi:[1,0,1]
	v_pk_fma_f32 v[30:31], v[140:141], s[30:31], v[30:31] op_sel_hi:[1,0,1]
	v_pk_fma_f32 v[16:17], v[222:223], s[30:31], v[16:17] op_sel_hi:[1,0,1]
	v_pk_fma_f32 v[18:19], v[142:143], s[30:31], v[18:19] op_sel_hi:[1,0,1]
	v_cvt_pk_bf16_f32 v220, v28, v29
	v_cvt_pk_bf16_f32 v221, v30, v31
	v_cvt_pk_bf16_f32 v222, v16, v17
	v_cvt_pk_bf16_f32 v223, v18, v19
	s_nop 1
	v_permlane16_swap_b32_e32 v220, v222
	v_permlane16_swap_b32_e32 v221, v223
	global_store_dwordx4 v136, v[220:223], s[6:7] offset:256
	s_waitcnt vmcnt(15)
	v_permlane16_swap_b32_e32 v224, v226
	v_permlane16_swap_b32_e32 v225, v227
	s_nop 0
	v_lshlrev_b32_e32 v140, 16, v225
	v_and_b32_e32 v141, 0xffff0000, v225
	v_and_b32_e32 v225, 0xffff0000, v224
	v_lshlrev_b32_e32 v224, 16, v224
	v_lshlrev_b32_e32 v142, 16, v227
	v_and_b32_e32 v143, 0xffff0000, v227
	v_and_b32_e32 v227, 0xffff0000, v226
	v_lshlrev_b32_e32 v226, 16, v226
	v_pk_fma_f32 v[24:25], v[224:225], s[30:31], v[24:25] op_sel_hi:[1,0,1]
	v_pk_fma_f32 v[26:27], v[140:141], s[30:31], v[26:27] op_sel_hi:[1,0,1]
	v_pk_fma_f32 v[20:21], v[226:227], s[30:31], v[20:21] op_sel_hi:[1,0,1]
	v_pk_fma_f32 v[22:23], v[142:143], s[30:31], v[22:23] op_sel_hi:[1,0,1]
	v_cvt_pk_bf16_f32 v224, v24, v25
	v_cvt_pk_bf16_f32 v225, v26, v27
	v_cvt_pk_bf16_f32 v226, v20, v21
	v_cvt_pk_bf16_f32 v227, v22, v23
	s_nop 1
	v_permlane16_swap_b32_e32 v224, v226
	v_permlane16_swap_b32_e32 v225, v227
	global_store_dwordx4 v136, v[224:227], s[6:7] offset:288
	s_waitcnt vmcnt(15)
	v_permlane16_swap_b32_e32 v228, v230
	v_permlane16_swap_b32_e32 v229, v231
	s_nop 0
	v_lshlrev_b32_e32 v140, 16, v229
	v_and_b32_e32 v141, 0xffff0000, v229
	v_and_b32_e32 v229, 0xffff0000, v228
	v_lshlrev_b32_e32 v228, 16, v228
	v_lshlrev_b32_e32 v142, 16, v231
	v_and_b32_e32 v143, 0xffff0000, v231
	v_and_b32_e32 v231, 0xffff0000, v230
	v_lshlrev_b32_e32 v230, 16, v230
	v_pk_fma_f32 v[40:41], v[228:229], s[30:31], v[40:41] op_sel_hi:[1,0,1]
	v_pk_fma_f32 v[42:43], v[140:141], s[30:31], v[42:43] op_sel_hi:[1,0,1]
	v_pk_fma_f32 v[32:33], v[230:231], s[30:31], v[32:33] op_sel_hi:[1,0,1]
	v_pk_fma_f32 v[34:35], v[142:143], s[30:31], v[34:35] op_sel_hi:[1,0,1]
	v_cvt_pk_bf16_f32 v228, v40, v41
	v_cvt_pk_bf16_f32 v229, v42, v43
	v_cvt_pk_bf16_f32 v230, v32, v33
	v_cvt_pk_bf16_f32 v231, v34, v35
	s_nop 1
	v_permlane16_swap_b32_e32 v228, v230
	v_permlane16_swap_b32_e32 v229, v231
	global_store_dwordx4 v138, v[228:231], s[6:7]
	s_waitcnt vmcnt(15)
	v_permlane16_swap_b32_e32 v232, v234
	v_permlane16_swap_b32_e32 v233, v235
	s_nop 0
	v_lshlrev_b32_e32 v140, 16, v233
	v_and_b32_e32 v141, 0xffff0000, v233
	v_and_b32_e32 v233, 0xffff0000, v232
	v_lshlrev_b32_e32 v232, 16, v232
	v_lshlrev_b32_e32 v142, 16, v235
	v_and_b32_e32 v143, 0xffff0000, v235
	v_and_b32_e32 v235, 0xffff0000, v234
	v_lshlrev_b32_e32 v234, 16, v234
	v_pk_fma_f32 v[44:45], v[232:233], s[30:31], v[44:45] op_sel_hi:[1,0,1]
	v_pk_fma_f32 v[46:47], v[140:141], s[30:31], v[46:47] op_sel_hi:[1,0,1]
	v_pk_fma_f32 v[36:37], v[234:235], s[30:31], v[36:37] op_sel_hi:[1,0,1]
	v_pk_fma_f32 v[38:39], v[142:143], s[30:31], v[38:39] op_sel_hi:[1,0,1]
	v_cvt_pk_bf16_f32 v232, v44, v45
	v_cvt_pk_bf16_f32 v233, v46, v47
	v_cvt_pk_bf16_f32 v234, v36, v37
	v_cvt_pk_bf16_f32 v235, v38, v39
	s_nop 1
	v_permlane16_swap_b32_e32 v232, v234
	v_permlane16_swap_b32_e32 v233, v235
	global_store_dwordx4 v138, v[232:235], s[6:7] offset:32
	s_waitcnt vmcnt(15)
	v_permlane16_swap_b32_e32 v236, v238
	v_permlane16_swap_b32_e32 v237, v239
	s_nop 0
	v_lshlrev_b32_e32 v140, 16, v237
	v_and_b32_e32 v141, 0xffff0000, v237
	v_and_b32_e32 v237, 0xffff0000, v236
	v_lshlrev_b32_e32 v236, 16, v236
	v_lshlrev_b32_e32 v142, 16, v239
	v_and_b32_e32 v143, 0xffff0000, v239
	v_and_b32_e32 v239, 0xffff0000, v238
	v_lshlrev_b32_e32 v238, 16, v238
	v_pk_fma_f32 v[8:9], v[236:237], s[30:31], v[8:9] op_sel_hi:[1,0,1]
	v_pk_fma_f32 v[10:11], v[140:141], s[30:31], v[10:11] op_sel_hi:[1,0,1]
	v_pk_fma_f32 v[0:1], v[238:239], s[30:31], v[0:1] op_sel_hi:[1,0,1]
	v_pk_fma_f32 v[2:3], v[142:143], s[30:31], v[2:3] op_sel_hi:[1,0,1]
	v_cvt_pk_bf16_f32 v236, v8, v9
	v_cvt_pk_bf16_f32 v237, v10, v11
	v_cvt_pk_bf16_f32 v238, v0, v1
	v_cvt_pk_bf16_f32 v239, v2, v3
	s_nop 1
	v_permlane16_swap_b32_e32 v236, v238
	v_permlane16_swap_b32_e32 v237, v239
	global_store_dwordx4 v138, v[236:239], s[6:7] offset:256
	s_waitcnt vmcnt(15)
	v_permlane16_swap_b32_e32 v240, v242
	v_permlane16_swap_b32_e32 v241, v243
	s_nop 0
	v_lshlrev_b32_e32 v140, 16, v241
	v_and_b32_e32 v141, 0xffff0000, v241
	v_and_b32_e32 v241, 0xffff0000, v240
	v_lshlrev_b32_e32 v240, 16, v240
	v_lshlrev_b32_e32 v142, 16, v243
	v_and_b32_e32 v143, 0xffff0000, v243
	v_and_b32_e32 v243, 0xffff0000, v242
	v_lshlrev_b32_e32 v242, 16, v242
	v_pk_fma_f32 v[12:13], v[240:241], s[30:31], v[12:13] op_sel_hi:[1,0,1]
	v_pk_fma_f32 v[14:15], v[140:141], s[30:31], v[14:15] op_sel_hi:[1,0,1]
	v_pk_fma_f32 v[4:5], v[242:243], s[30:31], v[4:5] op_sel_hi:[1,0,1]
	v_pk_fma_f32 v[6:7], v[142:143], s[30:31], v[6:7] op_sel_hi:[1,0,1]
	v_cvt_pk_bf16_f32 v240, v12, v13
	v_cvt_pk_bf16_f32 v241, v14, v15
	v_cvt_pk_bf16_f32 v242, v4, v5
	v_cvt_pk_bf16_f32 v243, v6, v7
	s_nop 1
	v_permlane16_swap_b32_e32 v240, v242
	v_permlane16_swap_b32_e32 v241, v243
	global_store_dwordx4 v138, v[240:243], s[6:7] offset:288
	s_andn2_b64 vcc, exec, s[0:1]
	s_mov_b32 s40, s56
	s_mov_b32 s42, s57
	s_cbranch_vccz .LBB0_758

.LBB0_1682:
	s_or_b64 exec, exec, s[44:45]
	s_lshl_b32 s98, s40, 1
	s_lshl_b32 s99, s42, 11
	s_add_i32 s98, s98, s99
	v_lshlrev_b32_e32 v132, 6, v152
	v_lshl_add_u32 v132, v153, 3, v132
	v_lshl_add_u32 v132, v155, 11, v132
	v_lshl_add_u32 v132, v145, 17, v132
	v_add_u32_e32 v132, s98, v132
	v_add_u32_e32 v133, 0x8000, v132
	v_add_u32_e32 v134, 0x10000, v132
	v_add_u32_e32 v135, 0x18000, v132
	v_add_u32_e32 v136, 0x40000, v132
	v_add_u32_e32 v137, 0x48000, v132
	v_add_u32_e32 v138, 0x50000, v132
	v_add_u32_e32 v139, 0x58000, v132
	v_bfe_u32 v133, v154, 4, 1
	v_mul_u32_u24_e32 v133, 0x7ff8, v133
	v_add_u32_e32 v132, v132, v133
	v_add_u32_e32 v134, v134, v133
	v_add_u32_e32 v136, v136, v133
	v_add_u32_e32 v138, v138, v133
	global_load_dwordx4 v[180:183], v132, s[6:7]
	global_load_dwordx4 v[184:187], v132, s[6:7] offset:32
	global_load_dwordx4 v[188:191], v132, s[6:7] offset:256
	global_load_dwordx4 v[192:195], v132, s[6:7] offset:288
	global_load_dwordx4 v[196:199], v134, s[6:7]
	global_load_dwordx4 v[200:203], v134, s[6:7] offset:32
	global_load_dwordx4 v[204:207], v134, s[6:7] offset:256
	global_load_dwordx4 v[208:211], v134, s[6:7] offset:288
	global_load_dwordx4 v[212:215], v136, s[6:7]
	global_load_dwordx4 v[216:219], v136, s[6:7] offset:32
	global_load_dwordx4 v[220:223], v136, s[6:7] offset:256
	global_load_dwordx4 v[224:227], v136, s[6:7] offset:288
	global_load_dwordx4 v[228:231], v138, s[6:7]
	global_load_dwordx4 v[232:235], v138, s[6:7] offset:32
	global_load_dwordx4 v[236:239], v138, s[6:7] offset:256
	global_load_dwordx4 v[240:243], v138, s[6:7] offset:288
	s_waitcnt vmcnt(15)
	v_permlane16_swap_b32_e32 v180, v182
	v_permlane16_swap_b32_e32 v181, v183
	s_nop 0
	v_lshlrev_b32_e32 v140, 16, v181
	v_and_b32_e32 v141, 0xffff0000, v181
	v_and_b32_e32 v181, 0xffff0000, v180
	v_lshlrev_b32_e32 v180, 16, v180
	v_lshlrev_b32_e32 v142, 16, v183
	v_and_b32_e32 v143, 0xffff0000, v183
	v_and_b32_e32 v183, 0xffff0000, v182
	v_lshlrev_b32_e32 v182, 16, v182
	v_pk_fma_f32 v[124:125], v[180:181], s[38:39], v[124:125] op_sel_hi:[1,0,1]
	v_pk_fma_f32 v[126:127], v[140:141], s[38:39], v[126:127] op_sel_hi:[1,0,1]
	v_pk_fma_f32 v[112:113], v[182:183], s[38:39], v[112:113] op_sel_hi:[1,0,1]
	v_pk_fma_f32 v[114:115], v[142:143], s[38:39], v[114:115] op_sel_hi:[1,0,1]
	v_cvt_pk_bf16_f32 v180, v124, v125
	v_cvt_pk_bf16_f32 v181, v126, v127
	v_cvt_pk_bf16_f32 v182, v112, v113
	v_cvt_pk_bf16_f32 v183, v114, v115
	s_nop 1
	v_permlane16_swap_b32_e32 v180, v182
	v_permlane16_swap_b32_e32 v181, v183
	global_store_dwordx4 v132, v[180:183], s[8:9]
	s_waitcnt vmcnt(15)
	v_permlane16_swap_b32_e32 v184, v186
	v_permlane16_swap_b32_e32 v185, v187
	s_nop 0
	v_lshlrev_b32_e32 v140, 16, v185
	v_and_b32_e32 v141, 0xffff0000, v185
	v_and_b32_e32 v185, 0xffff0000, v184
	v_lshlrev_b32_e32 v184, 16, v184
	v_lshlrev_b32_e32 v142, 16, v187
	v_and_b32_e32 v143, 0xffff0000, v187
	v_and_b32_e32 v187, 0xffff0000, v186
	v_lshlrev_b32_e32 v186, 16, v186
	v_pk_fma_f32 v[120:121], v[184:185], s[38:39], v[120:121] op_sel_hi:[1,0,1]
	v_pk_fma_f32 v[122:123], v[140:141], s[38:39], v[122:123] op_sel_hi:[1,0,1]
	v_pk_fma_f32 v[116:117], v[186:187], s[38:39], v[116:117] op_sel_hi:[1,0,1]
	v_pk_fma_f32 v[118:119], v[142:143], s[38:39], v[118:119] op_sel_hi:[1,0,1]
	v_cvt_pk_bf16_f32 v184, v120, v121
	v_cvt_pk_bf16_f32 v185, v122, v123
	v_cvt_pk_bf16_f32 v186, v116, v117
	v_cvt_pk_bf16_f32 v187, v118, v119
	s_nop 1
	v_permlane16_swap_b32_e32 v184, v186
	v_permlane16_swap_b32_e32 v185, v187
	global_store_dwordx4 v132, v[184:187], s[8:9] offset:32
	s_waitcnt vmcnt(15)
	v_permlane16_swap_b32_e32 v188, v190
	v_permlane16_swap_b32_e32 v189, v191
	s_nop 0
	v_lshlrev_b32_e32 v140, 16, v189
	v_and_b32_e32 v141, 0xffff0000, v189
	v_and_b32_e32 v189, 0xffff0000, v188
	v_lshlrev_b32_e32 v188, 16, v188
	v_lshlrev_b32_e32 v142, 16, v191
	v_and_b32_e32 v143, 0xffff0000, v191
	v_and_b32_e32 v191, 0xffff0000, v190
	v_lshlrev_b32_e32 v190, 16, v190
	v_pk_fma_f32 v[92:93], v[188:189], s[38:39], v[92:93] op_sel_hi:[1,0,1]
	v_pk_fma_f32 v[94:95], v[140:141], s[38:39], v[94:95] op_sel_hi:[1,0,1]
	v_pk_fma_f32 v[80:81], v[190:191], s[38:39], v[80:81] op_sel_hi:[1,0,1]
	v_pk_fma_f32 v[82:83], v[142:143], s[38:39], v[82:83] op_sel_hi:[1,0,1]
	v_cvt_pk_bf16_f32 v188, v92, v93
	v_cvt_pk_bf16_f32 v189, v94, v95
	v_cvt_pk_bf16_f32 v190, v80, v81
	v_cvt_pk_bf16_f32 v191, v82, v83
	s_nop 1
	v_permlane16_swap_b32_e32 v188, v190
	v_permlane16_swap_b32_e32 v189, v191
	global_store_dwordx4 v132, v[188:191], s[8:9] offset:256
	s_waitcnt vmcnt(15)
	v_permlane16_swap_b32_e32 v192, v194
	v_permlane16_swap_b32_e32 v193, v195
	s_nop 0
	v_lshlrev_b32_e32 v140, 16, v193
	v_and_b32_e32 v141, 0xffff0000, v193
	v_and_b32_e32 v193, 0xffff0000, v192
	v_lshlrev_b32_e32 v192, 16, v192
	v_lshlrev_b32_e32 v142, 16, v195
	v_and_b32_e32 v143, 0xffff0000, v195
	v_and_b32_e32 v195, 0xffff0000, v194
	v_lshlrev_b32_e32 v194, 16, v194
	v_pk_fma_f32 v[88:89], v[192:193], s[38:39], v[88:89] op_sel_hi:[1,0,1]
	v_pk_fma_f32 v[90:91], v[140:141], s[38:39], v[90:91] op_sel_hi:[1,0,1]
	v_pk_fma_f32 v[84:85], v[194:195], s[38:39], v[84:85] op_sel_hi:[1,0,1]
	v_pk_fma_f32 v[86:87], v[142:143], s[38:39], v[86:87] op_sel_hi:[1,0,1]
	v_cvt_pk_bf16_f32 v192, v88, v89
	v_cvt_pk_bf16_f32 v193, v90, v91
	v_cvt_pk_bf16_f32 v194, v84, v85
	v_cvt_pk_bf16_f32 v195, v86, v87
	s_nop 1
	v_permlane16_swap_b32_e32 v192, v194
	v_permlane16_swap_b32_e32 v193, v195
	global_store_dwordx4 v132, v[192:195], s[8:9] offset:288
	s_waitcnt vmcnt(15)
	v_permlane16_swap_b32_e32 v196, v198
	v_permlane16_swap_b32_e32 v197, v199
	s_nop 0
	v_lshlrev_b32_e32 v140, 16, v197
	v_and_b32_e32 v141, 0xffff0000, v197
	v_and_b32_e32 v197, 0xffff0000, v196
	v_lshlrev_b32_e32 v196, 16, v196
	v_lshlrev_b32_e32 v142, 16, v199
	v_and_b32_e32 v143, 0xffff0000, v199
	v_and_b32_e32 v199, 0xffff0000, v198
	v_lshlrev_b32_e32 v198, 16, v198
	v_pk_fma_f32 v[104:105], v[196:197], s[38:39], v[104:105] op_sel_hi:[1,0,1]
	v_pk_fma_f32 v[106:107], v[140:141], s[38:39], v[106:107] op_sel_hi:[1,0,1]
	v_pk_fma_f32 v[96:97], v[198:199], s[38:39], v[96:97] op_sel_hi:[1,0,1]
	v_pk_fma_f32 v[98:99], v[142:143], s[38:39], v[98:99] op_sel_hi:[1,0,1]
	v_cvt_pk_bf16_f32 v196, v104, v105
	v_cvt_pk_bf16_f32 v197, v106, v107
	v_cvt_pk_bf16_f32 v198, v96, v97
	v_cvt_pk_bf16_f32 v199, v98, v99
	s_nop 1
	v_permlane16_swap_b32_e32 v196, v198
	v_permlane16_swap_b32_e32 v197, v199
	global_store_dwordx4 v134, v[196:199], s[8:9]
	s_waitcnt vmcnt(15)
	v_permlane16_swap_b32_e32 v200, v202
	v_permlane16_swap_b32_e32 v201, v203
	s_nop 0
	v_lshlrev_b32_e32 v140, 16, v201
	v_and_b32_e32 v141, 0xffff0000, v201
	v_and_b32_e32 v201, 0xffff0000, v200
	v_lshlrev_b32_e32 v200, 16, v200
	v_lshlrev_b32_e32 v142, 16, v203
	v_and_b32_e32 v143, 0xffff0000, v203
	v_and_b32_e32 v203, 0xffff0000, v202
	v_lshlrev_b32_e32 v202, 16, v202
	v_pk_fma_f32 v[108:109], v[200:201], s[38:39], v[108:109] op_sel_hi:[1,0,1]
	v_pk_fma_f32 v[110:111], v[140:141], s[38:39], v[110:111] op_sel_hi:[1,0,1]
	v_pk_fma_f32 v[100:101], v[202:203], s[38:39], v[100:101] op_sel_hi:[1,0,1]
	v_pk_fma_f32 v[102:103], v[142:143], s[38:39], v[102:103] op_sel_hi:[1,0,1]
	v_cvt_pk_bf16_f32 v200, v108, v109
	v_cvt_pk_bf16_f32 v201, v110, v111
	v_cvt_pk_bf16_f32 v202, v100, v101
	v_cvt_pk_bf16_f32 v203, v102, v103
	s_nop 1
	v_permlane16_swap_b32_e32 v200, v202
	v_permlane16_swap_b32_e32 v201, v203
	global_store_dwordx4 v134, v[200:203], s[8:9] offset:32
	s_waitcnt vmcnt(15)
	v_permlane16_swap_b32_e32 v204, v206
	v_permlane16_swap_b32_e32 v205, v207
	s_nop 0
	v_lshlrev_b32_e32 v140, 16, v205
	v_and_b32_e32 v141, 0xffff0000, v205
	v_and_b32_e32 v205, 0xffff0000, v204
	v_lshlrev_b32_e32 v204, 16, v204
	v_lshlrev_b32_e32 v142, 16, v207
	v_and_b32_e32 v143, 0xffff0000, v207
	v_and_b32_e32 v207, 0xffff0000, v206
	v_lshlrev_b32_e32 v206, 16, v206
	v_pk_fma_f32 v[72:73], v[204:205], s[38:39], v[72:73] op_sel_hi:[1,0,1]
	v_pk_fma_f32 v[74:75], v[140:141], s[38:39], v[74:75] op_sel_hi:[1,0,1]
	v_pk_fma_f32 v[64:65], v[206:207], s[38:39], v[64:65] op_sel_hi:[1,0,1]
	v_pk_fma_f32 v[66:67], v[142:143], s[38:39], v[66:67] op_sel_hi:[1,0,1]
	v_cvt_pk_bf16_f32 v204, v72, v73
	v_cvt_pk_bf16_f32 v205, v74, v75
	v_cvt_pk_bf16_f32 v206, v64, v65
	v_cvt_pk_bf16_f32 v207, v66, v67
	s_nop 1
	v_permlane16_swap_b32_e32 v204, v206
	v_permlane16_swap_b32_e32 v205, v207
	global_store_dwordx4 v134, v[204:207], s[8:9] offset:256
	s_waitcnt vmcnt(15)
	v_permlane16_swap_b32_e32 v208, v210
	v_permlane16_swap_b32_e32 v209, v211
	s_nop 0
	v_lshlrev_b32_e32 v140, 16, v209
	v_and_b32_e32 v141, 0xffff0000, v209
	v_and_b32_e32 v209, 0xffff0000, v208
	v_lshlrev_b32_e32 v208, 16, v208
	v_lshlrev_b32_e32 v142, 16, v211
	v_and_b32_e32 v143, 0xffff0000, v211
	v_and_b32_e32 v211, 0xffff0000, v210
	v_lshlrev_b32_e32 v210, 16, v210
	v_pk_fma_f32 v[76:77], v[208:209], s[38:39], v[76:77] op_sel_hi:[1,0,1]
	v_pk_fma_f32 v[78:79], v[140:141], s[38:39], v[78:79] op_sel_hi:[1,0,1]
	v_pk_fma_f32 v[68:69], v[210:211], s[38:39], v[68:69] op_sel_hi:[1,0,1]
	v_pk_fma_f32 v[70:71], v[142:143], s[38:39], v[70:71] op_sel_hi:[1,0,1]
	v_cvt_pk_bf16_f32 v208, v76, v77
	v_cvt_pk_bf16_f32 v209, v78, v79
	v_cvt_pk_bf16_f32 v210, v68, v69
	v_cvt_pk_bf16_f32 v211, v70, v71
	s_nop 1
	v_permlane16_swap_b32_e32 v208, v210
	v_permlane16_swap_b32_e32 v209, v211
	global_store_dwordx4 v134, v[208:211], s[8:9] offset:288
	s_waitcnt vmcnt(15)
	v_permlane16_swap_b32_e32 v212, v214
	v_permlane16_swap_b32_e32 v213, v215
	s_nop 0
	v_lshlrev_b32_e32 v140, 16, v213
	v_and_b32_e32 v141, 0xffff0000, v213
	v_and_b32_e32 v213, 0xffff0000, v212
	v_lshlrev_b32_e32 v212, 16, v212
	v_lshlrev_b32_e32 v142, 16, v215
	v_and_b32_e32 v143, 0xffff0000, v215
	v_and_b32_e32 v215, 0xffff0000, v214
	v_lshlrev_b32_e32 v214, 16, v214
	v_pk_fma_f32 v[60:61], v[212:213], s[38:39], v[60:61] op_sel_hi:[1,0,1]
	v_pk_fma_f32 v[62:63], v[140:141], s[38:39], v[62:63] op_sel_hi:[1,0,1]
	v_pk_fma_f32 v[48:49], v[214:215], s[38:39], v[48:49] op_sel_hi:[1,0,1]
	v_pk_fma_f32 v[50:51], v[142:143], s[38:39], v[50:51] op_sel_hi:[1,0,1]
	v_cvt_pk_bf16_f32 v212, v60, v61
	v_cvt_pk_bf16_f32 v213, v62, v63
	v_cvt_pk_bf16_f32 v214, v48, v49
	v_cvt_pk_bf16_f32 v215, v50, v51
	s_nop 1
	v_permlane16_swap_b32_e32 v212, v214
	v_permlane16_swap_b32_e32 v213, v215
	global_store_dwordx4 v136, v[212:215], s[8:9]
	s_waitcnt vmcnt(15)
	v_permlane16_swap_b32_e32 v216, v218
	v_permlane16_swap_b32_e32 v217, v219
	s_nop 0
	v_lshlrev_b32_e32 v140, 16, v217
	v_and_b32_e32 v141, 0xffff0000, v217
	v_and_b32_e32 v217, 0xffff0000, v216
	v_lshlrev_b32_e32 v216, 16, v216
	v_lshlrev_b32_e32 v142, 16, v219
	v_and_b32_e32 v143, 0xffff0000, v219
	v_and_b32_e32 v219, 0xffff0000, v218
	v_lshlrev_b32_e32 v218, 16, v218
	v_pk_fma_f32 v[56:57], v[216:217], s[38:39], v[56:57] op_sel_hi:[1,0,1]
	v_pk_fma_f32 v[58:59], v[140:141], s[38:39], v[58:59] op_sel_hi:[1,0,1]
	v_pk_fma_f32 v[52:53], v[218:219], s[38:39], v[52:53] op_sel_hi:[1,0,1]
	v_pk_fma_f32 v[54:55], v[142:143], s[38:39], v[54:55] op_sel_hi:[1,0,1]
	v_cvt_pk_bf16_f32 v216, v56, v57
	v_cvt_pk_bf16_f32 v217, v58, v59
	v_cvt_pk_bf16_f32 v218, v52, v53
	v_cvt_pk_bf16_f32 v219, v54, v55
	s_nop 1
	v_permlane16_swap_b32_e32 v216, v218
	v_permlane16_swap_b32_e32 v217, v219
	global_store_dwordx4 v136, v[216:219], s[8:9] offset:32
	s_waitcnt vmcnt(15)
	v_permlane16_swap_b32_e32 v220, v222
	v_permlane16_swap_b32_e32 v221, v223
	s_nop 0
	v_lshlrev_b32_e32 v140, 16, v221
	v_and_b32_e32 v141, 0xffff0000, v221
	v_and_b32_e32 v221, 0xffff0000, v220
	v_lshlrev_b32_e32 v220, 16, v220
	v_lshlrev_b32_e32 v142, 16, v223
	v_and_b32_e32 v143, 0xffff0000, v223
	v_and_b32_e32 v223, 0xffff0000, v222
	v_lshlrev_b32_e32 v222, 16, v222
	v_pk_fma_f32 v[28:29], v[220:221], s[38:39], v[28:29] op_sel_hi:[1,0,1]
	v_pk_fma_f32 v[30:31], v[140:141], s[38:39], v[30:31] op_sel_hi:[1,0,1]
	v_pk_fma_f32 v[16:17], v[222:223], s[38:39], v[16:17] op_sel_hi:[1,0,1]
	v_pk_fma_f32 v[18:19], v[142:143], s[38:39], v[18:19] op_sel_hi:[1,0,1]
	v_cvt_pk_bf16_f32 v220, v28, v29
	v_cvt_pk_bf16_f32 v221, v30, v31
	v_cvt_pk_bf16_f32 v222, v16, v17
	v_cvt_pk_bf16_f32 v223, v18, v19
	s_nop 1
	v_permlane16_swap_b32_e32 v220, v222
	v_permlane16_swap_b32_e32 v221, v223
	global_store_dwordx4 v136, v[220:223], s[8:9] offset:256
	s_waitcnt vmcnt(15)
	v_permlane16_swap_b32_e32 v224, v226
	v_permlane16_swap_b32_e32 v225, v227
	s_nop 0
	v_lshlrev_b32_e32 v140, 16, v225
	v_and_b32_e32 v141, 0xffff0000, v225
	v_and_b32_e32 v225, 0xffff0000, v224
	v_lshlrev_b32_e32 v224, 16, v224
	v_lshlrev_b32_e32 v142, 16, v227
	v_and_b32_e32 v143, 0xffff0000, v227
	v_and_b32_e32 v227, 0xffff0000, v226
	v_lshlrev_b32_e32 v226, 16, v226
	v_pk_fma_f32 v[24:25], v[224:225], s[38:39], v[24:25] op_sel_hi:[1,0,1]
	v_pk_fma_f32 v[26:27], v[140:141], s[38:39], v[26:27] op_sel_hi:[1,0,1]
	v_pk_fma_f32 v[20:21], v[226:227], s[38:39], v[20:21] op_sel_hi:[1,0,1]
	v_pk_fma_f32 v[22:23], v[142:143], s[38:39], v[22:23] op_sel_hi:[1,0,1]
	v_cvt_pk_bf16_f32 v224, v24, v25
	v_cvt_pk_bf16_f32 v225, v26, v27
	v_cvt_pk_bf16_f32 v226, v20, v21
	v_cvt_pk_bf16_f32 v227, v22, v23
	s_nop 1
	v_permlane16_swap_b32_e32 v224, v226
	v_permlane16_swap_b32_e32 v225, v227
	global_store_dwordx4 v136, v[224:227], s[8:9] offset:288
	s_waitcnt vmcnt(15)
	v_permlane16_swap_b32_e32 v228, v230
	v_permlane16_swap_b32_e32 v229, v231
	s_nop 0
	v_lshlrev_b32_e32 v140, 16, v229
	v_and_b32_e32 v141, 0xffff0000, v229
	v_and_b32_e32 v229, 0xffff0000, v228
	v_lshlrev_b32_e32 v228, 16, v228
	v_lshlrev_b32_e32 v142, 16, v231
	v_and_b32_e32 v143, 0xffff0000, v231
	v_and_b32_e32 v231, 0xffff0000, v230
	v_lshlrev_b32_e32 v230, 16, v230
	v_pk_fma_f32 v[40:41], v[228:229], s[38:39], v[40:41] op_sel_hi:[1,0,1]
	v_pk_fma_f32 v[42:43], v[140:141], s[38:39], v[42:43] op_sel_hi:[1,0,1]
	v_pk_fma_f32 v[32:33], v[230:231], s[38:39], v[32:33] op_sel_hi:[1,0,1]
	v_pk_fma_f32 v[34:35], v[142:143], s[38:39], v[34:35] op_sel_hi:[1,0,1]
	v_cvt_pk_bf16_f32 v228, v40, v41
	v_cvt_pk_bf16_f32 v229, v42, v43
	v_cvt_pk_bf16_f32 v230, v32, v33
	v_cvt_pk_bf16_f32 v231, v34, v35
	s_nop 1
	v_permlane16_swap_b32_e32 v228, v230
	v_permlane16_swap_b32_e32 v229, v231
	global_store_dwordx4 v138, v[228:231], s[8:9]
	s_waitcnt vmcnt(15)
	v_permlane16_swap_b32_e32 v232, v234
	v_permlane16_swap_b32_e32 v233, v235
	s_nop 0
	v_lshlrev_b32_e32 v140, 16, v233
	v_and_b32_e32 v141, 0xffff0000, v233
	v_and_b32_e32 v233, 0xffff0000, v232
	v_lshlrev_b32_e32 v232, 16, v232
	v_lshlrev_b32_e32 v142, 16, v235
	v_and_b32_e32 v143, 0xffff0000, v235
	v_and_b32_e32 v235, 0xffff0000, v234
	v_lshlrev_b32_e32 v234, 16, v234
	v_pk_fma_f32 v[44:45], v[232:233], s[38:39], v[44:45] op_sel_hi:[1,0,1]
	v_pk_fma_f32 v[46:47], v[140:141], s[38:39], v[46:47] op_sel_hi:[1,0,1]
	v_pk_fma_f32 v[36:37], v[234:235], s[38:39], v[36:37] op_sel_hi:[1,0,1]
	v_pk_fma_f32 v[38:39], v[142:143], s[38:39], v[38:39] op_sel_hi:[1,0,1]
	v_cvt_pk_bf16_f32 v232, v44, v45
	v_cvt_pk_bf16_f32 v233, v46, v47
	v_cvt_pk_bf16_f32 v234, v36, v37
	v_cvt_pk_bf16_f32 v235, v38, v39
	s_nop 1
	v_permlane16_swap_b32_e32 v232, v234
	v_permlane16_swap_b32_e32 v233, v235
	global_store_dwordx4 v138, v[232:235], s[8:9] offset:32
	s_waitcnt vmcnt(15)
	v_permlane16_swap_b32_e32 v236, v238
	v_permlane16_swap_b32_e32 v237, v239
	s_nop 0
	v_lshlrev_b32_e32 v140, 16, v237
	v_and_b32_e32 v141, 0xffff0000, v237
	v_and_b32_e32 v237, 0xffff0000, v236
	v_lshlrev_b32_e32 v236, 16, v236
	v_lshlrev_b32_e32 v142, 16, v239
	v_and_b32_e32 v143, 0xffff0000, v239
	v_and_b32_e32 v239, 0xffff0000, v238
	v_lshlrev_b32_e32 v238, 16, v238
	v_pk_fma_f32 v[8:9], v[236:237], s[38:39], v[8:9] op_sel_hi:[1,0,1]
	v_pk_fma_f32 v[10:11], v[140:141], s[38:39], v[10:11] op_sel_hi:[1,0,1]
	v_pk_fma_f32 v[0:1], v[238:239], s[38:39], v[0:1] op_sel_hi:[1,0,1]
	v_pk_fma_f32 v[2:3], v[142:143], s[38:39], v[2:3] op_sel_hi:[1,0,1]
	v_cvt_pk_bf16_f32 v236, v8, v9
	v_cvt_pk_bf16_f32 v237, v10, v11
	v_cvt_pk_bf16_f32 v238, v0, v1
	v_cvt_pk_bf16_f32 v239, v2, v3
	s_nop 1
	v_permlane16_swap_b32_e32 v236, v238
	v_permlane16_swap_b32_e32 v237, v239
	global_store_dwordx4 v138, v[236:239], s[8:9] offset:256
	s_waitcnt vmcnt(15)
	v_permlane16_swap_b32_e32 v240, v242
	v_permlane16_swap_b32_e32 v241, v243
	s_nop 0
	v_lshlrev_b32_e32 v140, 16, v241
	v_and_b32_e32 v141, 0xffff0000, v241
	v_and_b32_e32 v241, 0xffff0000, v240
	v_lshlrev_b32_e32 v240, 16, v240
	v_lshlrev_b32_e32 v142, 16, v243
	v_and_b32_e32 v143, 0xffff0000, v243
	v_and_b32_e32 v243, 0xffff0000, v242
	v_lshlrev_b32_e32 v242, 16, v242
	v_pk_fma_f32 v[12:13], v[240:241], s[38:39], v[12:13] op_sel_hi:[1,0,1]
	v_pk_fma_f32 v[14:15], v[140:141], s[38:39], v[14:15] op_sel_hi:[1,0,1]
	v_pk_fma_f32 v[4:5], v[242:243], s[38:39], v[4:5] op_sel_hi:[1,0,1]
	v_pk_fma_f32 v[6:7], v[142:143], s[38:39], v[6:7] op_sel_hi:[1,0,1]
	v_cvt_pk_bf16_f32 v240, v12, v13
	v_cvt_pk_bf16_f32 v241, v14, v15
	v_cvt_pk_bf16_f32 v242, v4, v5
	v_cvt_pk_bf16_f32 v243, v6, v7
	s_nop 1
	v_permlane16_swap_b32_e32 v240, v242
	v_permlane16_swap_b32_e32 v241, v243
	global_store_dwordx4 v138, v[240:243], s[8:9] offset:288
	s_andn2_b64 vcc, exec, s[0:1]
	s_mov_b32 s43, s61
	s_mov_b32 s42, s62
	s_cbranch_vccz .LBB0_1691

.LBB0_1863:
	s_or_b64 exec, exec, s[38:39]
	s_lshl_b32 s98, s60, 1
	s_lshl_b32 s99, s61, 11
	s_add_i32 s98, s98, s99
	v_lshlrev_b32_e32 v132, 6, v155
	v_lshl_add_u32 v132, v156, 3, v132
	v_lshl_add_u32 v132, v157, 11, v132
	v_lshl_add_u32 v132, v153, 17, v132
	v_add_u32_e32 v132, s98, v132
	v_add_u32_e32 v133, 0x8000, v132
	v_add_u32_e32 v134, 0x10000, v132
	v_add_u32_e32 v135, 0x18000, v132
	v_add_u32_e32 v136, 0x40000, v132
	v_add_u32_e32 v137, 0x48000, v132
	v_add_u32_e32 v138, 0x50000, v132
	v_add_u32_e32 v139, 0x58000, v132
	v_bfe_u32 v133, v154, 4, 1
	v_mul_u32_u24_e32 v133, 0x7ff8, v133
	v_add_u32_e32 v132, v132, v133
	v_add_u32_e32 v134, v134, v133
	v_add_u32_e32 v136, v136, v133
	v_add_u32_e32 v138, v138, v133
	global_load_dwordx4 v[180:183], v132, s[8:9]
	global_load_dwordx4 v[184:187], v132, s[8:9] offset:32
	global_load_dwordx4 v[188:191], v132, s[8:9] offset:256
	global_load_dwordx4 v[192:195], v132, s[8:9] offset:288
	global_load_dwordx4 v[196:199], v134, s[8:9]
	global_load_dwordx4 v[200:203], v134, s[8:9] offset:32
	global_load_dwordx4 v[204:207], v134, s[8:9] offset:256
	global_load_dwordx4 v[208:211], v134, s[8:9] offset:288
	global_load_dwordx4 v[212:215], v136, s[8:9]
	global_load_dwordx4 v[216:219], v136, s[8:9] offset:32
	global_load_dwordx4 v[220:223], v136, s[8:9] offset:256
	global_load_dwordx4 v[224:227], v136, s[8:9] offset:288
	global_load_dwordx4 v[228:231], v138, s[8:9]
	global_load_dwordx4 v[232:235], v138, s[8:9] offset:32
	global_load_dwordx4 v[236:239], v138, s[8:9] offset:256
	global_load_dwordx4 v[240:243], v138, s[8:9] offset:288
	s_waitcnt vmcnt(15)
	v_permlane16_swap_b32_e32 v180, v182
	v_permlane16_swap_b32_e32 v181, v183
	s_nop 0
	v_lshlrev_b32_e32 v140, 16, v181
	v_and_b32_e32 v141, 0xffff0000, v181
	v_and_b32_e32 v181, 0xffff0000, v180
	v_lshlrev_b32_e32 v180, 16, v180
	v_lshlrev_b32_e32 v142, 16, v183
	v_and_b32_e32 v143, 0xffff0000, v183
	v_and_b32_e32 v183, 0xffff0000, v182
	v_lshlrev_b32_e32 v182, 16, v182
	v_pk_fma_f32 v[124:125], v[180:181], s[30:31], v[124:125] op_sel_hi:[1,0,1]
	v_pk_fma_f32 v[126:127], v[140:141], s[30:31], v[126:127] op_sel_hi:[1,0,1]
	v_pk_fma_f32 v[112:113], v[182:183], s[30:31], v[112:113] op_sel_hi:[1,0,1]
	v_pk_fma_f32 v[114:115], v[142:143], s[30:31], v[114:115] op_sel_hi:[1,0,1]
	v_cvt_pk_bf16_f32 v180, v124, v125
	v_cvt_pk_bf16_f32 v181, v126, v127
	v_cvt_pk_bf16_f32 v182, v112, v113
	v_cvt_pk_bf16_f32 v183, v114, v115
	s_nop 1
	v_permlane16_swap_b32_e32 v180, v182
	v_permlane16_swap_b32_e32 v181, v183
	global_store_dwordx4 v132, v[180:183], s[6:7]
	s_waitcnt vmcnt(15)
	v_permlane16_swap_b32_e32 v184, v186
	v_permlane16_swap_b32_e32 v185, v187
	s_nop 0
	v_lshlrev_b32_e32 v140, 16, v185
	v_and_b32_e32 v141, 0xffff0000, v185
	v_and_b32_e32 v185, 0xffff0000, v184
	v_lshlrev_b32_e32 v184, 16, v184
	v_lshlrev_b32_e32 v142, 16, v187
	v_and_b32_e32 v143, 0xffff0000, v187
	v_and_b32_e32 v187, 0xffff0000, v186
	v_lshlrev_b32_e32 v186, 16, v186
	v_pk_fma_f32 v[120:121], v[184:185], s[30:31], v[120:121] op_sel_hi:[1,0,1]
	v_pk_fma_f32 v[122:123], v[140:141], s[30:31], v[122:123] op_sel_hi:[1,0,1]
	v_pk_fma_f32 v[116:117], v[186:187], s[30:31], v[116:117] op_sel_hi:[1,0,1]
	v_pk_fma_f32 v[118:119], v[142:143], s[30:31], v[118:119] op_sel_hi:[1,0,1]
	v_cvt_pk_bf16_f32 v184, v120, v121
	v_cvt_pk_bf16_f32 v185, v122, v123
	v_cvt_pk_bf16_f32 v186, v116, v117
	v_cvt_pk_bf16_f32 v187, v118, v119
	s_nop 1
	v_permlane16_swap_b32_e32 v184, v186
	v_permlane16_swap_b32_e32 v185, v187
	global_store_dwordx4 v132, v[184:187], s[6:7] offset:32
	s_waitcnt vmcnt(15)
	v_permlane16_swap_b32_e32 v188, v190
	v_permlane16_swap_b32_e32 v189, v191
	s_nop 0
	v_lshlrev_b32_e32 v140, 16, v189
	v_and_b32_e32 v141, 0xffff0000, v189
	v_and_b32_e32 v189, 0xffff0000, v188
	v_lshlrev_b32_e32 v188, 16, v188
	v_lshlrev_b32_e32 v142, 16, v191
	v_and_b32_e32 v143, 0xffff0000, v191
	v_and_b32_e32 v191, 0xffff0000, v190
	v_lshlrev_b32_e32 v190, 16, v190
	v_pk_fma_f32 v[92:93], v[188:189], s[30:31], v[92:93] op_sel_hi:[1,0,1]
	v_pk_fma_f32 v[94:95], v[140:141], s[30:31], v[94:95] op_sel_hi:[1,0,1]
	v_pk_fma_f32 v[80:81], v[190:191], s[30:31], v[80:81] op_sel_hi:[1,0,1]
	v_pk_fma_f32 v[82:83], v[142:143], s[30:31], v[82:83] op_sel_hi:[1,0,1]
	v_cvt_pk_bf16_f32 v188, v92, v93
	v_cvt_pk_bf16_f32 v189, v94, v95
	v_cvt_pk_bf16_f32 v190, v80, v81
	v_cvt_pk_bf16_f32 v191, v82, v83
	s_nop 1
	v_permlane16_swap_b32_e32 v188, v190
	v_permlane16_swap_b32_e32 v189, v191
	global_store_dwordx4 v132, v[188:191], s[6:7] offset:256
	s_waitcnt vmcnt(15)
	v_permlane16_swap_b32_e32 v192, v194
	v_permlane16_swap_b32_e32 v193, v195
	s_nop 0
	v_lshlrev_b32_e32 v140, 16, v193
	v_and_b32_e32 v141, 0xffff0000, v193
	v_and_b32_e32 v193, 0xffff0000, v192
	v_lshlrev_b32_e32 v192, 16, v192
	v_lshlrev_b32_e32 v142, 16, v195
	v_and_b32_e32 v143, 0xffff0000, v195
	v_and_b32_e32 v195, 0xffff0000, v194
	v_lshlrev_b32_e32 v194, 16, v194
	v_pk_fma_f32 v[88:89], v[192:193], s[30:31], v[88:89] op_sel_hi:[1,0,1]
	v_pk_fma_f32 v[90:91], v[140:141], s[30:31], v[90:91] op_sel_hi:[1,0,1]
	v_pk_fma_f32 v[84:85], v[194:195], s[30:31], v[84:85] op_sel_hi:[1,0,1]
	v_pk_fma_f32 v[86:87], v[142:143], s[30:31], v[86:87] op_sel_hi:[1,0,1]
	v_cvt_pk_bf16_f32 v192, v88, v89
	v_cvt_pk_bf16_f32 v193, v90, v91
	v_cvt_pk_bf16_f32 v194, v84, v85
	v_cvt_pk_bf16_f32 v195, v86, v87
	s_nop 1
	v_permlane16_swap_b32_e32 v192, v194
	v_permlane16_swap_b32_e32 v193, v195
	global_store_dwordx4 v132, v[192:195], s[6:7] offset:288
	s_waitcnt vmcnt(15)
	v_permlane16_swap_b32_e32 v196, v198
	v_permlane16_swap_b32_e32 v197, v199
	s_nop 0
	v_lshlrev_b32_e32 v140, 16, v197
	v_and_b32_e32 v141, 0xffff0000, v197
	v_and_b32_e32 v197, 0xffff0000, v196
	v_lshlrev_b32_e32 v196, 16, v196
	v_lshlrev_b32_e32 v142, 16, v199
	v_and_b32_e32 v143, 0xffff0000, v199
	v_and_b32_e32 v199, 0xffff0000, v198
	v_lshlrev_b32_e32 v198, 16, v198
	v_pk_fma_f32 v[104:105], v[196:197], s[30:31], v[104:105] op_sel_hi:[1,0,1]
	v_pk_fma_f32 v[106:107], v[140:141], s[30:31], v[106:107] op_sel_hi:[1,0,1]
	v_pk_fma_f32 v[96:97], v[198:199], s[30:31], v[96:97] op_sel_hi:[1,0,1]
	v_pk_fma_f32 v[98:99], v[142:143], s[30:31], v[98:99] op_sel_hi:[1,0,1]
	v_cvt_pk_bf16_f32 v196, v104, v105
	v_cvt_pk_bf16_f32 v197, v106, v107
	v_cvt_pk_bf16_f32 v198, v96, v97
	v_cvt_pk_bf16_f32 v199, v98, v99
	s_nop 1
	v_permlane16_swap_b32_e32 v196, v198
	v_permlane16_swap_b32_e32 v197, v199
	global_store_dwordx4 v134, v[196:199], s[6:7]
	s_waitcnt vmcnt(15)
	v_permlane16_swap_b32_e32 v200, v202
	v_permlane16_swap_b32_e32 v201, v203
	s_nop 0
	v_lshlrev_b32_e32 v140, 16, v201
	v_and_b32_e32 v141, 0xffff0000, v201
	v_and_b32_e32 v201, 0xffff0000, v200
	v_lshlrev_b32_e32 v200, 16, v200
	v_lshlrev_b32_e32 v142, 16, v203
	v_and_b32_e32 v143, 0xffff0000, v203
	v_and_b32_e32 v203, 0xffff0000, v202
	v_lshlrev_b32_e32 v202, 16, v202
	v_pk_fma_f32 v[108:109], v[200:201], s[30:31], v[108:109] op_sel_hi:[1,0,1]
	v_pk_fma_f32 v[110:111], v[140:141], s[30:31], v[110:111] op_sel_hi:[1,0,1]
	v_pk_fma_f32 v[100:101], v[202:203], s[30:31], v[100:101] op_sel_hi:[1,0,1]
	v_pk_fma_f32 v[102:103], v[142:143], s[30:31], v[102:103] op_sel_hi:[1,0,1]
	v_cvt_pk_bf16_f32 v200, v108, v109
	v_cvt_pk_bf16_f32 v201, v110, v111
	v_cvt_pk_bf16_f32 v202, v100, v101
	v_cvt_pk_bf16_f32 v203, v102, v103
	s_nop 1
	v_permlane16_swap_b32_e32 v200, v202
	v_permlane16_swap_b32_e32 v201, v203
	global_store_dwordx4 v134, v[200:203], s[6:7] offset:32
	s_waitcnt vmcnt(15)
	v_permlane16_swap_b32_e32 v204, v206
	v_permlane16_swap_b32_e32 v205, v207
	s_nop 0
	v_lshlrev_b32_e32 v140, 16, v205
	v_and_b32_e32 v141, 0xffff0000, v205
	v_and_b32_e32 v205, 0xffff0000, v204
	v_lshlrev_b32_e32 v204, 16, v204
	v_lshlrev_b32_e32 v142, 16, v207
	v_and_b32_e32 v143, 0xffff0000, v207
	v_and_b32_e32 v207, 0xffff0000, v206
	v_lshlrev_b32_e32 v206, 16, v206
	v_pk_fma_f32 v[72:73], v[204:205], s[30:31], v[72:73] op_sel_hi:[1,0,1]
	v_pk_fma_f32 v[74:75], v[140:141], s[30:31], v[74:75] op_sel_hi:[1,0,1]
	v_pk_fma_f32 v[64:65], v[206:207], s[30:31], v[64:65] op_sel_hi:[1,0,1]
	v_pk_fma_f32 v[66:67], v[142:143], s[30:31], v[66:67] op_sel_hi:[1,0,1]
	v_cvt_pk_bf16_f32 v204, v72, v73
	v_cvt_pk_bf16_f32 v205, v74, v75
	v_cvt_pk_bf16_f32 v206, v64, v65
	v_cvt_pk_bf16_f32 v207, v66, v67
	s_nop 1
	v_permlane16_swap_b32_e32 v204, v206
	v_permlane16_swap_b32_e32 v205, v207
	global_store_dwordx4 v134, v[204:207], s[6:7] offset:256
	s_waitcnt vmcnt(15)
	v_permlane16_swap_b32_e32 v208, v210
	v_permlane16_swap_b32_e32 v209, v211
	s_nop 0
	v_lshlrev_b32_e32 v140, 16, v209
	v_and_b32_e32 v141, 0xffff0000, v209
	v_and_b32_e32 v209, 0xffff0000, v208
	v_lshlrev_b32_e32 v208, 16, v208
	v_lshlrev_b32_e32 v142, 16, v211
	v_and_b32_e32 v143, 0xffff0000, v211
	v_and_b32_e32 v211, 0xffff0000, v210
	v_lshlrev_b32_e32 v210, 16, v210
	v_pk_fma_f32 v[76:77], v[208:209], s[30:31], v[76:77] op_sel_hi:[1,0,1]
	v_pk_fma_f32 v[78:79], v[140:141], s[30:31], v[78:79] op_sel_hi:[1,0,1]
	v_pk_fma_f32 v[68:69], v[210:211], s[30:31], v[68:69] op_sel_hi:[1,0,1]
	v_pk_fma_f32 v[70:71], v[142:143], s[30:31], v[70:71] op_sel_hi:[1,0,1]
	v_cvt_pk_bf16_f32 v208, v76, v77
	v_cvt_pk_bf16_f32 v209, v78, v79
	v_cvt_pk_bf16_f32 v210, v68, v69
	v_cvt_pk_bf16_f32 v211, v70, v71
	s_nop 1
	v_permlane16_swap_b32_e32 v208, v210
	v_permlane16_swap_b32_e32 v209, v211
	global_store_dwordx4 v134, v[208:211], s[6:7] offset:288
	s_waitcnt vmcnt(15)
	v_permlane16_swap_b32_e32 v212, v214
	v_permlane16_swap_b32_e32 v213, v215
	s_nop 0
	v_lshlrev_b32_e32 v140, 16, v213
	v_and_b32_e32 v141, 0xffff0000, v213
	v_and_b32_e32 v213, 0xffff0000, v212
	v_lshlrev_b32_e32 v212, 16, v212
	v_lshlrev_b32_e32 v142, 16, v215
	v_and_b32_e32 v143, 0xffff0000, v215
	v_and_b32_e32 v215, 0xffff0000, v214
	v_lshlrev_b32_e32 v214, 16, v214
	v_pk_fma_f32 v[60:61], v[212:213], s[30:31], v[60:61] op_sel_hi:[1,0,1]
	v_pk_fma_f32 v[62:63], v[140:141], s[30:31], v[62:63] op_sel_hi:[1,0,1]
	v_pk_fma_f32 v[48:49], v[214:215], s[30:31], v[48:49] op_sel_hi:[1,0,1]
	v_pk_fma_f32 v[50:51], v[142:143], s[30:31], v[50:51] op_sel_hi:[1,0,1]
	v_cvt_pk_bf16_f32 v212, v60, v61
	v_cvt_pk_bf16_f32 v213, v62, v63
	v_cvt_pk_bf16_f32 v214, v48, v49
	v_cvt_pk_bf16_f32 v215, v50, v51
	s_nop 1
	v_permlane16_swap_b32_e32 v212, v214
	v_permlane16_swap_b32_e32 v213, v215
	global_store_dwordx4 v136, v[212:215], s[6:7]
	s_waitcnt vmcnt(15)
	v_permlane16_swap_b32_e32 v216, v218
	v_permlane16_swap_b32_e32 v217, v219
	s_nop 0
	v_lshlrev_b32_e32 v140, 16, v217
	v_and_b32_e32 v141, 0xffff0000, v217
	v_and_b32_e32 v217, 0xffff0000, v216
	v_lshlrev_b32_e32 v216, 16, v216
	v_lshlrev_b32_e32 v142, 16, v219
	v_and_b32_e32 v143, 0xffff0000, v219
	v_and_b32_e32 v219, 0xffff0000, v218
	v_lshlrev_b32_e32 v218, 16, v218
	v_pk_fma_f32 v[56:57], v[216:217], s[30:31], v[56:57] op_sel_hi:[1,0,1]
	v_pk_fma_f32 v[58:59], v[140:141], s[30:31], v[58:59] op_sel_hi:[1,0,1]
	v_pk_fma_f32 v[52:53], v[218:219], s[30:31], v[52:53] op_sel_hi:[1,0,1]
	v_pk_fma_f32 v[54:55], v[142:143], s[30:31], v[54:55] op_sel_hi:[1,0,1]
	v_cvt_pk_bf16_f32 v216, v56, v57
	v_cvt_pk_bf16_f32 v217, v58, v59
	v_cvt_pk_bf16_f32 v218, v52, v53
	v_cvt_pk_bf16_f32 v219, v54, v55
	s_nop 1
	v_permlane16_swap_b32_e32 v216, v218
	v_permlane16_swap_b32_e32 v217, v219
	global_store_dwordx4 v136, v[216:219], s[6:7] offset:32
	s_waitcnt vmcnt(15)
	v_permlane16_swap_b32_e32 v220, v222
	v_permlane16_swap_b32_e32 v221, v223
	s_nop 0
	v_lshlrev_b32_e32 v140, 16, v221
	v_and_b32_e32 v141, 0xffff0000, v221
	v_and_b32_e32 v221, 0xffff0000, v220
	v_lshlrev_b32_e32 v220, 16, v220
	v_lshlrev_b32_e32 v142, 16, v223
	v_and_b32_e32 v143, 0xffff0000, v223
	v_and_b32_e32 v223, 0xffff0000, v222
	v_lshlrev_b32_e32 v222, 16, v222
	v_pk_fma_f32 v[28:29], v[220:221], s[30:31], v[28:29] op_sel_hi:[1,0,1]
	v_pk_fma_f32 v[30:31], v[140:141], s[30:31], v[30:31] op_sel_hi:[1,0,1]
	v_pk_fma_f32 v[16:17], v[222:223], s[30:31], v[16:17] op_sel_hi:[1,0,1]
	v_pk_fma_f32 v[18:19], v[142:143], s[30:31], v[18:19] op_sel_hi:[1,0,1]
	v_cvt_pk_bf16_f32 v220, v28, v29
	v_cvt_pk_bf16_f32 v221, v30, v31
	v_cvt_pk_bf16_f32 v222, v16, v17
	v_cvt_pk_bf16_f32 v223, v18, v19
	s_nop 1
	v_permlane16_swap_b32_e32 v220, v222
	v_permlane16_swap_b32_e32 v221, v223
	global_store_dwordx4 v136, v[220:223], s[6:7] offset:256
	s_waitcnt vmcnt(15)
	v_permlane16_swap_b32_e32 v224, v226
	v_permlane16_swap_b32_e32 v225, v227
	s_nop 0
	v_lshlrev_b32_e32 v140, 16, v225
	v_and_b32_e32 v141, 0xffff0000, v225
	v_and_b32_e32 v225, 0xffff0000, v224
	v_lshlrev_b32_e32 v224, 16, v224
	v_lshlrev_b32_e32 v142, 16, v227
	v_and_b32_e32 v143, 0xffff0000, v227
	v_and_b32_e32 v227, 0xffff0000, v226
	v_lshlrev_b32_e32 v226, 16, v226
	v_pk_fma_f32 v[24:25], v[224:225], s[30:31], v[24:25] op_sel_hi:[1,0,1]
	v_pk_fma_f32 v[26:27], v[140:141], s[30:31], v[26:27] op_sel_hi:[1,0,1]
	v_pk_fma_f32 v[20:21], v[226:227], s[30:31], v[20:21] op_sel_hi:[1,0,1]
	v_pk_fma_f32 v[22:23], v[142:143], s[30:31], v[22:23] op_sel_hi:[1,0,1]
	v_cvt_pk_bf16_f32 v224, v24, v25
	v_cvt_pk_bf16_f32 v225, v26, v27
	v_cvt_pk_bf16_f32 v226, v20, v21
	v_cvt_pk_bf16_f32 v227, v22, v23
	s_nop 1
	v_permlane16_swap_b32_e32 v224, v226
	v_permlane16_swap_b32_e32 v225, v227
	global_store_dwordx4 v136, v[224:227], s[6:7] offset:288
	s_waitcnt vmcnt(15)
	v_permlane16_swap_b32_e32 v228, v230
	v_permlane16_swap_b32_e32 v229, v231
	s_nop 0
	v_lshlrev_b32_e32 v140, 16, v229
	v_and_b32_e32 v141, 0xffff0000, v229
	v_and_b32_e32 v229, 0xffff0000, v228
	v_lshlrev_b32_e32 v228, 16, v228
	v_lshlrev_b32_e32 v142, 16, v231
	v_and_b32_e32 v143, 0xffff0000, v231
	v_and_b32_e32 v231, 0xffff0000, v230
	v_lshlrev_b32_e32 v230, 16, v230
	v_pk_fma_f32 v[40:41], v[228:229], s[30:31], v[40:41] op_sel_hi:[1,0,1]
	v_pk_fma_f32 v[42:43], v[140:141], s[30:31], v[42:43] op_sel_hi:[1,0,1]
	v_pk_fma_f32 v[32:33], v[230:231], s[30:31], v[32:33] op_sel_hi:[1,0,1]
	v_pk_fma_f32 v[34:35], v[142:143], s[30:31], v[34:35] op_sel_hi:[1,0,1]
	v_cvt_pk_bf16_f32 v228, v40, v41
	v_cvt_pk_bf16_f32 v229, v42, v43
	v_cvt_pk_bf16_f32 v230, v32, v33
	v_cvt_pk_bf16_f32 v231, v34, v35
	s_nop 1
	v_permlane16_swap_b32_e32 v228, v230
	v_permlane16_swap_b32_e32 v229, v231
	global_store_dwordx4 v138, v[228:231], s[6:7]
	s_waitcnt vmcnt(15)
	v_permlane16_swap_b32_e32 v232, v234
	v_permlane16_swap_b32_e32 v233, v235
	s_nop 0
	v_lshlrev_b32_e32 v140, 16, v233
	v_and_b32_e32 v141, 0xffff0000, v233
	v_and_b32_e32 v233, 0xffff0000, v232
	v_lshlrev_b32_e32 v232, 16, v232
	v_lshlrev_b32_e32 v142, 16, v235
	v_and_b32_e32 v143, 0xffff0000, v235
	v_and_b32_e32 v235, 0xffff0000, v234
	v_lshlrev_b32_e32 v234, 16, v234
	v_pk_fma_f32 v[44:45], v[232:233], s[30:31], v[44:45] op_sel_hi:[1,0,1]
	v_pk_fma_f32 v[46:47], v[140:141], s[30:31], v[46:47] op_sel_hi:[1,0,1]
	v_pk_fma_f32 v[36:37], v[234:235], s[30:31], v[36:37] op_sel_hi:[1,0,1]
	v_pk_fma_f32 v[38:39], v[142:143], s[30:31], v[38:39] op_sel_hi:[1,0,1]
	v_cvt_pk_bf16_f32 v232, v44, v45
	v_cvt_pk_bf16_f32 v233, v46, v47
	v_cvt_pk_bf16_f32 v234, v36, v37
	v_cvt_pk_bf16_f32 v235, v38, v39
	s_nop 1
	v_permlane16_swap_b32_e32 v232, v234
	v_permlane16_swap_b32_e32 v233, v235
	global_store_dwordx4 v138, v[232:235], s[6:7] offset:32
	s_waitcnt vmcnt(15)
	v_permlane16_swap_b32_e32 v236, v238
	v_permlane16_swap_b32_e32 v237, v239
	s_nop 0
	v_lshlrev_b32_e32 v140, 16, v237
	v_and_b32_e32 v141, 0xffff0000, v237
	v_and_b32_e32 v237, 0xffff0000, v236
	v_lshlrev_b32_e32 v236, 16, v236
	v_lshlrev_b32_e32 v142, 16, v239
	v_and_b32_e32 v143, 0xffff0000, v239
	v_and_b32_e32 v239, 0xffff0000, v238
	v_lshlrev_b32_e32 v238, 16, v238
	v_pk_fma_f32 v[8:9], v[236:237], s[30:31], v[8:9] op_sel_hi:[1,0,1]
	v_pk_fma_f32 v[10:11], v[140:141], s[30:31], v[10:11] op_sel_hi:[1,0,1]
	v_pk_fma_f32 v[0:1], v[238:239], s[30:31], v[0:1] op_sel_hi:[1,0,1]
	v_pk_fma_f32 v[2:3], v[142:143], s[30:31], v[2:3] op_sel_hi:[1,0,1]
	v_cvt_pk_bf16_f32 v236, v8, v9
	v_cvt_pk_bf16_f32 v237, v10, v11
	v_cvt_pk_bf16_f32 v238, v0, v1
	v_cvt_pk_bf16_f32 v239, v2, v3
	s_nop 1
	v_permlane16_swap_b32_e32 v236, v238
	v_permlane16_swap_b32_e32 v237, v239
	global_store_dwordx4 v138, v[236:239], s[6:7] offset:256
	s_waitcnt vmcnt(15)
	v_permlane16_swap_b32_e32 v240, v242
	v_permlane16_swap_b32_e32 v241, v243
	s_nop 0
	v_lshlrev_b32_e32 v140, 16, v241
	v_and_b32_e32 v141, 0xffff0000, v241
	v_and_b32_e32 v241, 0xffff0000, v240
	v_lshlrev_b32_e32 v240, 16, v240
	v_lshlrev_b32_e32 v142, 16, v243
	v_and_b32_e32 v143, 0xffff0000, v243
	v_and_b32_e32 v243, 0xffff0000, v242
	v_lshlrev_b32_e32 v242, 16, v242
	v_pk_fma_f32 v[12:13], v[240:241], s[30:31], v[12:13] op_sel_hi:[1,0,1]
	v_pk_fma_f32 v[14:15], v[140:141], s[30:31], v[14:15] op_sel_hi:[1,0,1]
	v_pk_fma_f32 v[4:5], v[242:243], s[30:31], v[4:5] op_sel_hi:[1,0,1]
	v_pk_fma_f32 v[6:7], v[142:143], s[30:31], v[6:7] op_sel_hi:[1,0,1]
	v_cvt_pk_bf16_f32 v240, v12, v13
	v_cvt_pk_bf16_f32 v241, v14, v15
	v_cvt_pk_bf16_f32 v242, v4, v5
	v_cvt_pk_bf16_f32 v243, v6, v7
	s_nop 1
	v_permlane16_swap_b32_e32 v240, v242
	v_permlane16_swap_b32_e32 v241, v243
	global_store_dwordx4 v138, v[240:243], s[6:7] offset:288
	s_andn2_b64 vcc, exec, s[0:1]
	s_mov_b32 s40, s56
	s_mov_b32 s42, s57
	s_cbranch_vccz .LBB0_1872
